# MLA_Q/MLA_KV tile loops: per-tile row-scale (rsqrt of sum-of-squares) load no longer waited in front of the tile's 16 prologue loads; math + LDS write deferred behind them
# baseline (speedup 1.0000x reference)
; DI int opaque_tid() { int t = threadIdx.x; asm volatile("" : "+v"(t)); return t; }
; DI void gemm_mainloop(const bf16* __restrict__ A, int lda, const bf16* __restrict__ Bt, int ldb, int K, int m0, int n0,
;                       bf16* As, bf16* Bs, f32x16& acc0, f32x16& acc1, f32x16& acc2, f32x16& acc3) {
;   const int tid = opaque_tid(), lane = tid & 63, w = tid >> 6, r = lane & 31, g = lane >> 5;
;   const int lrow = tid >> 3, lcc = (tid & 7) * 8;
;   const bf16* ap = A + (size_t)(m0 + lrow) * lda + lcc;
;   const bf16* bp = Bt + (size_t)(n0 + lrow) * ldb + lcc;
;   GTile t0, t1;
;   asm volatile("" ::: "memory");
;   const int nkt = K >> 6;
;   int kb = ((((m0 >> 7) * 5 + (n0 >> 7) * 3) >> 1) % nkt) << 6;
;     ...
;   gt_load(t0, ap, bp, lda, ldb, KW(0));
;   gt_load(t1, ap, bp, lda, ldb, KW(64));
; #pragma unroll
;   for (int i = 0; i < 16; ++i) { acc0[i] = 0.f; acc1[i] = 0.f; acc2[i] = 0.f; acc3[i] = 0.f; }
;   bf16* asw = As + lrow * LDT + lcc;
;   bf16* bsw = Bs + lrow * LDT + lcc;
;     ...
;     if (EPI == EPI_MLA_Q || EPI == EPI_MLA_KV) {
;       __syncthreads();
;       if (tid < 128) {
;         const float* rp = (const float*)(ws + OFF_RSS) + (size_t)(m0 + tid) * 8;
;         const float ssq = (EPI == EPI_MLA_Q) ? ((rp[0] + rp[1]) + rp[2]) : (rp[3] + rp[4]);
;         rs[tid] = rsqrtf(ssq / (float)K + 1e-6f);
;       }
.LBB0_323:
	s_mul_hi_i32 s0, s42, 0x2aaaaaab
	s_lshr_b32 s1, s0, 31
	s_ashr_i32 s14, s0, 1
	s_add_i32 s14, s14, s1
	s_lshl_b32 s15, s14, 7
	s_barrier
	s_and_saveexec_b64 s[12:13], s[6:7]
	s_cbranch_execz .LBB0_325
	v_add_u32_e32 v246, s15, v104
	v_ashrrev_i32_e32 v247, 31, v246
	v_lshlrev_b64 v[246:247], 5, v[246:247]
	v_lshl_add_u64 v[246:247], s[8:9], 0, v[246:247]
	global_load_dwordx3 v[246:248], v[246:247], off
.LBB0_325:
	s_or_b64 exec, exec, s[12:13]
	v_mov_b32_e32 v40, v160
	s_mul_i32 s43, s14, 0x600
	v_ashrrev_i32_e32 v41, 3, v40
	v_lshlrev_b32_e32 v2, 4, v40
	v_and_b32_e32 v68, 0x70, v2
	v_subrev_u32_e32 v2, s43, v41
	v_add_u32_e32 v2, s4, v2
	v_add_u32_e32 v0, s15, v41
	v_add_u32_e32 v2, 0xffffffa0, v2
	v_mad_i64_i32 v[0:1], s[0:1], v0, s19, v[72:73]
	v_mad_i64_i32 v[2:3], s[0:1], v2, s20, v[74:75]
	s_mul_i32 s0, s14, 0xffffffe1
	s_add_i32 s0, s16, s0
	s_ashr_i32 s0, s0, 1
	s_mul_hi_i32 s1, s0, 0x2aaaaaab
	s_lshr_b32 s12, s1, 31
	s_add_i32 s1, s1, s12
	s_mul_i32 s1, s1, 6
	s_sub_i32 s0, s0, s1
	s_lshl_b32 s12, s0, 6
	s_ashr_i32 s13, s12, 31
	v_lshl_add_u64 v[0:1], v[0:1], 0, v[68:69]
	s_lshl_b64 s[12:13], s[12:13], 1
	v_lshl_add_u64 v[76:77], v[0:1], 0, s[12:13]
	v_add_co_u32_e32 v8, vcc, s21, v76
	v_lshl_add_u64 v[2:3], v[2:3], 0, v[68:69]
	s_nop 0
	v_addc_co_u32_e32 v9, vcc, 0, v77, vcc
	v_add_co_u32_e32 v10, vcc, s28, v76
	v_lshl_add_u64 v[78:79], v[2:3], 0, s[12:13]
	s_nop 0
	v_addc_co_u32_e32 v11, vcc, 0, v77, vcc
	v_add_co_u32_e32 v16, vcc, s29, v76
	global_load_dwordx4 v[0:3], v[8:9], off
	global_load_dwordx4 v[4:7], v[10:11], off
	v_addc_co_u32_e32 v17, vcc, 0, v77, vcc
	v_add_co_u32_e32 v20, vcc, s34, v78
	global_load_dwordx4 v[8:11], v[76:77], off
	global_load_dwordx4 v[12:15], v[78:79], off
	v_addc_co_u32_e32 v21, vcc, 0, v79, vcc
	v_add_co_u32_e32 v24, vcc, s35, v78
	global_load_dwordx4 v[16:19], v[16:17], off
	s_nop 0
	global_load_dwordx4 v[20:23], v[20:21], off
	v_addc_co_u32_e32 v25, vcc, 0, v79, vcc
	v_add_co_u32_e32 v28, vcc, s38, v78
	s_mul_i32 s1, s14, 0xfffffa00
	s_nop 0
	v_addc_co_u32_e32 v29, vcc, 0, v79, vcc
	global_load_dwordx4 v[24:27], v[24:25], off
	s_nop 0
	global_load_dwordx4 v[28:31], v[28:29], off
	s_add_i32 s44, s4, s1
	s_add_i32 s12, s44, 0xffffffa0
	s_cmp_lt_i32 s0, 5
	s_cselect_b32 s47, 0, -1
	s_cselect_b32 s46, 0, 0xfffffd00
	v_lshl_add_u64 v[32:33], v[76:77], 0, s[46:47]
	v_add_co_u32_e32 v36, vcc, s21, v32
	v_lshl_add_u64 v[34:35], v[78:79], 0, s[46:47]
	s_nop 0
	v_addc_co_u32_e32 v37, vcc, 0, v33, vcc
	v_add_co_u32_e32 v38, vcc, s28, v32
	v_mad_u64_u32 v[64:65], s[46:47], v41, s39, v[68:69]
	s_nop 0
	v_addc_co_u32_e32 v39, vcc, 0, v33, vcc
	global_load_dwordx4 v[80:83], v[36:37], off offset:128
	global_load_dwordx4 v[84:87], v[38:39], off offset:128
	v_add_co_u32_e32 v36, vcc, s29, v32
	global_load_dwordx4 v[88:91], v[32:33], off offset:128
	global_load_dwordx4 v[92:95], v[34:35], off offset:128
	v_addc_co_u32_e32 v37, vcc, 0, v33, vcc
	v_add_co_u32_e32 v32, vcc, s34, v34
	s_cmp_lt_i32 s0, 4
	s_nop 0
	v_addc_co_u32_e32 v33, vcc, 0, v35, vcc
	global_load_dwordx4 v[96:99], v[36:37], off offset:128
	global_load_dwordx4 v[100:103], v[32:33], off offset:128
	v_add_co_u32_e32 v32, vcc, s35, v34
	s_cselect_b32 s47, 0, -1
	s_nop 0
	v_addc_co_u32_e32 v33, vcc, 0, v35, vcc
	v_add_co_u32_e32 v34, vcc, s38, v34
	s_cselect_b32 s46, 0, 0xfffffd00
	s_nop 0
	v_addc_co_u32_e32 v35, vcc, 0, v35, vcc
	global_load_dwordx4 v[124:127], v[32:33], off offset:128
	global_load_dwordx4 v[130:133], v[34:35], off offset:128
	s_movk_i32 s100, 0x80
	v_cmp_gt_u32_e64 s[100:101], s100, v160
	s_and_saveexec_b64 s[98:99], s[100:101]
	s_cbranch_execz .Lmy_rss_q
	s_waitcnt vmcnt(16)
	v_add_f32_e32 v246, v246, v247
	v_add_f32_e32 v246, v246, v248
	v_div_scale_f32 v247, s[100:101], s17, s17, v246
	v_rcp_f32_e32 v248, v247
	v_div_scale_f32 v249, vcc, v246, s17, v246
	v_fma_f32 v250, -v247, v248, 1.0
	v_fmac_f32_e32 v248, v250, v248
	v_mul_f32_e32 v250, v249, v248
	v_fma_f32 v251, -v247, v250, v249
	v_fmac_f32_e32 v250, v251, v248
	v_fma_f32 v247, -v247, v250, v249
	v_div_fmas_f32 v247, v247, v248, v250
	v_div_fixup_f32 v246, v247, s17, v246
	v_add_f32_e32 v246, 0x358637bd, v246
	v_mul_f32_e32 v247, 0x4b800000, v246
	v_cmp_gt_f32_e32 vcc, s18, v246
	s_nop 1
	v_cndmask_b32_e32 v246, v246, v247, vcc
	v_rsq_f32_e32 v246, v246
	s_nop 0
	v_mul_f32_e32 v247, 0x45800000, v246
	v_cndmask_b32_e32 v246, v246, v247, vcc
	ds_write_b32 v106, v246 offset:40960
; #define MFMA(a, b, c) __builtin_amdgcn_mfma_f32_32x32x16_bf16((a), (b), (c), 0, 0, 0)
; DI void gt_compute(const bf16* asr, const bf16* bsr, f32x16& acc0, f32x16& acc1, f32x16& acc2, f32x16& acc3) {
;   bf16x8 a[4], b0[4], b1[4], b2[4], b3[4];
; #pragma unroll
;   for (int kk = 0; kk < 4; ++kk) {
;     a[kk] = *(const bf16x8*)(asr + kk * 16);
;     b0[kk] = *(const bf16x8*)(bsr + kk * 16);
;     b1[kk] = *(const bf16x8*)(bsr + 32 * LDT + kk * 16);
;     b2[kk] = *(const bf16x8*)(bsr + 64 * LDT + kk * 16);
;     b3[kk] = *(const bf16x8*)(bsr + 96 * LDT + kk * 16);
;   }
;   __builtin_amdgcn_sched_barrier(0);
;   __builtin_amdgcn_s_setprio(2);
; #pragma unroll
;   for (int kk = 0; kk < 4; ++kk) {
;     acc0 = MFMA(a[kk], b0[kk], acc0); acc1 = MFMA(a[kk], b1[kk], acc1); acc2 = MFMA(a[kk], b2[kk], acc2); acc3 = MFMA(a[kk], b3[kk], acc3);
;   }
;   __builtin_amdgcn_s_setprio(0);
;   __builtin_amdgcn_sched_barrier(0);
; DI void gemm_mainloop(const bf16* __restrict__ A, int lda, const bf16* __restrict__ Bt, int ldb, int K, int m0, int n0,
;                       bf16* As, bf16* Bs, f32x16& acc0, f32x16& acc1, f32x16& acc2, f32x16& acc3) {
;     ...
;   for (int k0 = 0; k0 < K; k0 += 128) {
;     __syncthreads();
;     gt_store(t0, asw, bsw);
;     __syncthreads();
;     if (k0 + 128 < K) gt_load(t0, ap, bp, lda, ldb, KW(k0 + 128));
;     gt_compute(asr, bsr, acc0, acc1, acc2, acc3);
;     __syncthreads();
;     gt_store(t1, asw, bsw);
;     __syncthreads();
;     if (k0 + 192 < K) gt_load(t1, ap, bp, lda, ldb, KW(k0 + 192));
;     gt_compute(asr, bsr, acc0, acc1, acc2, acc3);
.Lmy_rss_q:
	s_or_b64 exec, exec, s[98:99]
	s_waitcnt lgkmcnt(0)
	s_barrier
	s_waitcnt vmcnt(13)
	ds_write_b128 v64, v[8:11]
	ds_write_b128 v64, v[0:3] offset:4608
	ds_write_b128 v64, v[4:7] offset:9216
	s_waitcnt vmcnt(11)
	ds_write_b128 v64, v[16:19] offset:13824
	ds_write_b128 v64, v[12:15] offset:18432
	s_waitcnt vmcnt(10)
	ds_write_b128 v64, v[20:23] offset:23040
	s_waitcnt vmcnt(9)
	ds_write_b128 v64, v[24:27] offset:27648
	s_waitcnt vmcnt(8)
	ds_write_b128 v64, v[28:31] offset:32256
	v_lshl_add_u64 v[0:1], v[76:77], 0, s[46:47]
	v_add_co_u32_e32 v4, vcc, s21, v0
	s_waitcnt lgkmcnt(0)
	s_nop 0
	v_addc_co_u32_e32 v5, vcc, 0, v1, vcc
	v_add_co_u32_e32 v6, vcc, s28, v0
	s_barrier
	s_nop 0
	v_addc_co_u32_e32 v7, vcc, 0, v1, vcc
	global_load_dwordx4 v[134:137], v[4:5], off offset:256
	global_load_dwordx4 v[138:141], v[6:7], off offset:256
	v_add_co_u32_e32 v4, vcc, s29, v0
	v_lshl_add_u64 v[2:3], v[78:79], 0, s[46:47]
	s_nop 0
	v_addc_co_u32_e32 v5, vcc, 0, v1, vcc
	global_load_dwordx4 v[142:145], v[0:1], off offset:256
	global_load_dwordx4 v[146:149], v[2:3], off offset:256
	v_add_co_u32_e32 v0, vcc, s34, v2
	s_nop 1
	v_addc_co_u32_e32 v1, vcc, 0, v3, vcc
	global_load_dwordx4 v[150:153], v[4:5], off offset:256
	global_load_dwordx4 v[154:157], v[0:1], off offset:256
	v_add_co_u32_e32 v0, vcc, s35, v2
	s_nop 1
	v_addc_co_u32_e32 v1, vcc, 0, v3, vcc
	v_add_co_u32_e32 v2, vcc, s38, v2
	s_nop 1
	v_addc_co_u32_e32 v3, vcc, 0, v3, vcc
	global_load_dwordx4 v[162:165], v[0:1], off offset:256
	global_load_dwordx4 v[166:169], v[2:3], off offset:256
	v_and_b32_e32 v1, 31, v40
	v_lshrrev_b32_e32 v0, 1, v40
	v_and_or_b32 v2, v0, s40, v1
	v_and_b32_e32 v0, 16, v0
	v_mad_u64_u32 v[66:67], s[46:47], v2, s39, v[0:1]
	v_mad_u32_u24 v65, v1, s39, v0
	ds_read_b128 v[0:3], v66
	ds_read_b128 v[170:173], v66 offset:32
	ds_read_b128 v[4:7], v65 offset:18432
	ds_read_b128 v[174:177], v65 offset:18464
	ds_read_b128 v[8:11], v65 offset:23040
	ds_read_b128 v[178:181], v65 offset:23072
	ds_read_b128 v[12:15], v65 offset:27648
	ds_read_b128 v[182:185], v65 offset:27680
	ds_read_b128 v[186:189], v65 offset:32256
	ds_read_b128 v[190:193], v65 offset:32288
	ds_read_b128 v[194:197], v66 offset:64
	ds_read_b128 v[198:201], v66 offset:96
	ds_read_b128 v[202:205], v65 offset:18496
	ds_read_b128 v[206:209], v65 offset:18528
	ds_read_b128 v[210:213], v65 offset:23104
	ds_read_b128 v[214:217], v65 offset:23136
	ds_read_b128 v[218:221], v65 offset:27712
	ds_read_b128 v[222:225], v65 offset:27744
	ds_read_b128 v[226:229], v65 offset:32320
	ds_read_b128 v[230:233], v65 offset:32352
	s_setprio 2
	s_waitcnt lgkmcnt(14)
	v_mfma_f32_32x32x16_bf16 v[48:63], v[0:3], v[4:7], 0
	v_mfma_f32_32x32x16_bf16 v[32:47], v[0:3], v[8:11], 0
	s_waitcnt lgkmcnt(13)
	v_mfma_f32_32x32x16_bf16 v[16:31], v[0:3], v[12:15], 0
	s_waitcnt lgkmcnt(11)
	v_mfma_f32_32x32x16_bf16 v[0:15], v[0:3], v[186:189], 0
	v_mfma_f32_32x32x16_bf16 v[48:63], v[170:173], v[174:177], v[48:63]
	v_mfma_f32_32x32x16_bf16 v[32:47], v[170:173], v[178:181], v[32:47]
	v_mfma_f32_32x32x16_bf16 v[16:31], v[170:173], v[182:185], v[16:31]
	s_waitcnt lgkmcnt(10)
	v_mfma_f32_32x32x16_bf16 v[0:15], v[170:173], v[190:193], v[0:15]
	s_waitcnt lgkmcnt(7)
	v_mfma_f32_32x32x16_bf16 v[48:63], v[194:197], v[202:205], v[48:63]
	s_waitcnt lgkmcnt(5)
	v_mfma_f32_32x32x16_bf16 v[32:47], v[194:197], v[210:213], v[32:47]
	s_waitcnt lgkmcnt(3)
	v_mfma_f32_32x32x16_bf16 v[16:31], v[194:197], v[218:221], v[16:31]
	s_waitcnt lgkmcnt(1)
	v_mfma_f32_32x32x16_bf16 v[0:15], v[194:197], v[226:229], v[0:15]
	v_mfma_f32_32x32x16_bf16 v[48:63], v[198:201], v[206:209], v[48:63]
	v_mfma_f32_32x32x16_bf16 v[32:47], v[198:201], v[214:217], v[32:47]
	v_mfma_f32_32x32x16_bf16 v[16:31], v[198:201], v[222:225], v[16:31]
	s_waitcnt lgkmcnt(0)
	v_mfma_f32_32x32x16_bf16 v[0:15], v[198:201], v[230:233], v[0:15]
	s_setprio 0
	s_cmp_lt_i32 s0, 3
	s_cselect_b32 s47, 0, -1
	s_cselect_b32 s46, 0, 0xfffffd00
	s_barrier
	s_waitcnt vmcnt(13)
	ds_write_b128 v64, v[88:91]
	ds_write_b128 v64, v[80:83] offset:4608
	ds_write_b128 v64, v[84:87] offset:9216
	s_waitcnt vmcnt(11)
	ds_write_b128 v64, v[96:99] offset:13824
	ds_write_b128 v64, v[92:95] offset:18432
	s_waitcnt vmcnt(10)
	ds_write_b128 v64, v[100:103] offset:23040
	s_waitcnt vmcnt(9)
	ds_write_b128 v64, v[124:127] offset:27648
	s_waitcnt vmcnt(8)
	ds_write_b128 v64, v[130:133] offset:32256
	v_lshl_add_u64 v[88:89], v[76:77], 0, s[46:47]
	v_add_co_u32_e32 v80, vcc, s21, v88
	v_lshl_add_u64 v[124:125], v[78:79], 0, s[46:47]
	s_nop 0
	v_addc_co_u32_e32 v81, vcc, 0, v89, vcc
	v_add_co_u32_e32 v84, vcc, s28, v88
	s_waitcnt lgkmcnt(0)
	s_nop 0
	v_addc_co_u32_e32 v85, vcc, 0, v89, vcc
	v_add_co_u32_e32 v96, vcc, s29, v88
	s_barrier
; #define MFMA(a, b, c) __builtin_amdgcn_mfma_f32_32x32x16_bf16((a), (b), (c), 0, 0, 0)
; DI void gt_compute(const bf16* asr, const bf16* bsr, f32x16& acc0, f32x16& acc1, f32x16& acc2, f32x16& acc3) {
;   bf16x8 a[4], b0[4], b1[4], b2[4], b3[4];
; #pragma unroll
;   for (int kk = 0; kk < 4; ++kk) {
;     a[kk] = *(const bf16x8*)(asr + kk * 16);
;     b0[kk] = *(const bf16x8*)(bsr + kk * 16);
;     b1[kk] = *(const bf16x8*)(bsr + 32 * LDT + kk * 16);
;     b2[kk] = *(const bf16x8*)(bsr + 64 * LDT + kk * 16);
;     b3[kk] = *(const bf16x8*)(bsr + 96 * LDT + kk * 16);
;   }
;   __builtin_amdgcn_sched_barrier(0);
;   __builtin_amdgcn_s_setprio(2);
; #pragma unroll
;   for (int kk = 0; kk < 4; ++kk) {
;     acc0 = MFMA(a[kk], b0[kk], acc0); acc1 = MFMA(a[kk], b1[kk], acc1); acc2 = MFMA(a[kk], b2[kk], acc2); acc3 = MFMA(a[kk], b3[kk], acc3);
;   }
;   __builtin_amdgcn_s_setprio(0);
;   __builtin_amdgcn_sched_barrier(0);
; DI void gemm_mainloop(const bf16* __restrict__ A, int lda, const bf16* __restrict__ Bt, int ldb, int K, int m0, int n0,
;                       bf16* As, bf16* Bs, f32x16& acc0, f32x16& acc1, f32x16& acc2, f32x16& acc3) {
;     ...
;   for (int k0 = 0; k0 < K; k0 += 128) {
;     __syncthreads();
;     gt_store(t0, asw, bsw);
;     __syncthreads();
;     if (k0 + 128 < K) gt_load(t0, ap, bp, lda, ldb, KW(k0 + 128));
;     gt_compute(asr, bsr, acc0, acc1, acc2, acc3);
;     __syncthreads();
;     gt_store(t1, asw, bsw);
;     __syncthreads();
;     if (k0 + 192 < K) gt_load(t1, ap, bp, lda, ldb, KW(k0 + 192));
;     gt_compute(asr, bsr, acc0, acc1, acc2, acc3);
	s_nop 0
	v_addc_co_u32_e32 v97, vcc, 0, v89, vcc
	v_add_co_u32_e32 v100, vcc, s34, v124
	s_nop 1
	v_addc_co_u32_e32 v101, vcc, 0, v125, vcc
	v_add_co_u32_e32 v126, vcc, s35, v124
	global_load_dwordx4 v[80:83], v[80:81], off offset:384
	s_nop 0
	global_load_dwordx4 v[84:87], v[84:85], off offset:384
	v_addc_co_u32_e32 v127, vcc, 0, v125, vcc
	v_add_co_u32_e32 v128, vcc, s38, v124
	global_load_dwordx4 v[88:91], v[88:89], off offset:384
	s_nop 0
	global_load_dwordx4 v[92:95], v[124:125], off offset:384
	s_nop 0
	global_load_dwordx4 v[96:99], v[96:97], off offset:384
	s_nop 0
	global_load_dwordx4 v[100:103], v[100:101], off offset:384
	v_addc_co_u32_e32 v129, vcc, 0, v125, vcc
	global_load_dwordx4 v[124:127], v[126:127], off offset:384
	s_nop 0
	global_load_dwordx4 v[130:133], v[128:129], off offset:384
	ds_read_b128 v[170:173], v66
	ds_read_b128 v[174:177], v66 offset:32
	ds_read_b128 v[178:181], v65 offset:18432
	ds_read_b128 v[182:185], v65 offset:18464
	ds_read_b128 v[186:189], v65 offset:23040
	ds_read_b128 v[190:193], v65 offset:23072
	ds_read_b128 v[194:197], v65 offset:27648
	ds_read_b128 v[198:201], v65 offset:27680
	ds_read_b128 v[202:205], v65 offset:32256
	ds_read_b128 v[206:209], v65 offset:32288
	ds_read_b128 v[210:213], v66 offset:64
	ds_read_b128 v[214:217], v66 offset:96
	ds_read_b128 v[218:221], v65 offset:18496
	ds_read_b128 v[222:225], v65 offset:18528
	ds_read_b128 v[226:229], v65 offset:23104
	ds_read_b128 v[230:233], v65 offset:23136
	ds_read_b128 v[234:237], v65 offset:27712
	ds_read_b128 v[238:241], v65 offset:27744
	ds_read_b128 v[242:245], v65 offset:32320
	ds_read_b128 v[246:249], v65 offset:32352
	s_setprio 2
	s_waitcnt lgkmcnt(14)
	v_mfma_f32_32x32x16_bf16 v[48:63], v[170:173], v[178:181], v[48:63]
	v_mfma_f32_32x32x16_bf16 v[32:47], v[170:173], v[186:189], v[32:47]
	s_waitcnt lgkmcnt(13)
	v_mfma_f32_32x32x16_bf16 v[16:31], v[170:173], v[194:197], v[16:31]
	s_waitcnt lgkmcnt(11)
	v_mfma_f32_32x32x16_bf16 v[0:15], v[170:173], v[202:205], v[0:15]
	v_mfma_f32_32x32x16_bf16 v[48:63], v[174:177], v[182:185], v[48:63]
	v_mfma_f32_32x32x16_bf16 v[32:47], v[174:177], v[190:193], v[32:47]
	v_mfma_f32_32x32x16_bf16 v[16:31], v[174:177], v[198:201], v[16:31]
	s_waitcnt lgkmcnt(10)
	v_mfma_f32_32x32x16_bf16 v[0:15], v[174:177], v[206:209], v[0:15]
	s_waitcnt lgkmcnt(7)
	v_mfma_f32_32x32x16_bf16 v[48:63], v[210:213], v[218:221], v[48:63]
	s_waitcnt lgkmcnt(5)
	v_mfma_f32_32x32x16_bf16 v[32:47], v[210:213], v[226:229], v[32:47]
	s_waitcnt lgkmcnt(3)
	v_mfma_f32_32x32x16_bf16 v[16:31], v[210:213], v[234:237], v[16:31]
	s_waitcnt lgkmcnt(1)
	v_mfma_f32_32x32x16_bf16 v[0:15], v[210:213], v[242:245], v[0:15]
	v_mfma_f32_32x32x16_bf16 v[48:63], v[214:217], v[222:225], v[48:63]
	v_mfma_f32_32x32x16_bf16 v[32:47], v[214:217], v[230:233], v[32:47]
	v_mfma_f32_32x32x16_bf16 v[16:31], v[214:217], v[238:241], v[16:31]
	s_waitcnt lgkmcnt(0)
	v_mfma_f32_32x32x16_bf16 v[0:15], v[214:217], v[246:249], v[0:15]
	s_setprio 0
	s_cmp_lt_i32 s0, 2
	s_cselect_b32 s47, 0, -1
	s_cselect_b32 s46, 0, 0xfffffd00
	v_lshl_add_u64 v[128:129], v[76:77], 0, s[46:47]
	s_barrier
	s_waitcnt vmcnt(13)
	ds_write_b128 v64, v[142:145]
	ds_write_b128 v64, v[134:137] offset:4608
	ds_write_b128 v64, v[138:141] offset:9216
	s_waitcnt vmcnt(11)
	ds_write_b128 v64, v[150:153] offset:13824
	ds_write_b128 v64, v[146:149] offset:18432
	s_waitcnt vmcnt(10)
	ds_write_b128 v64, v[154:157] offset:23040
	s_waitcnt vmcnt(9)
	ds_write_b128 v64, v[162:165] offset:27648
	s_waitcnt vmcnt(8)
	ds_write_b128 v64, v[166:169] offset:32256
	v_add_co_u32_e32 v134, vcc, s21, v128
	v_lshl_add_u64 v[162:163], v[78:79], 0, s[46:47]
	s_nop 0
	v_addc_co_u32_e32 v135, vcc, 0, v129, vcc
	v_add_co_u32_e32 v138, vcc, s28, v128
	s_waitcnt lgkmcnt(0)
	s_nop 0
	v_addc_co_u32_e32 v139, vcc, 0, v129, vcc
	v_add_co_u32_e32 v150, vcc, s29, v128
	s_barrier
	s_nop 0
	v_addc_co_u32_e32 v151, vcc, 0, v129, vcc
	global_load_dwordx4 v[134:137], v[134:135], off offset:512
	s_nop 0
	global_load_dwordx4 v[138:141], v[138:139], off offset:512
	s_nop 0
	global_load_dwordx4 v[142:145], v[128:129], off offset:512
	global_load_dwordx4 v[146:149], v[162:163], off offset:512
	v_add_co_u32_e32 v128, vcc, s34, v162
	s_nop 1
	v_addc_co_u32_e32 v129, vcc, 0, v163, vcc
	global_load_dwordx4 v[150:153], v[150:151], off offset:512
	s_nop 0
	global_load_dwordx4 v[154:157], v[128:129], off offset:512
	v_add_co_u32_e32 v128, vcc, s35, v162
	s_nop 1
	v_addc_co_u32_e32 v129, vcc, 0, v163, vcc
	v_add_co_u32_e32 v166, vcc, s38, v162
	s_nop 1
	v_addc_co_u32_e32 v167, vcc, 0, v163, vcc
	global_load_dwordx4 v[162:165], v[128:129], off offset:512
	s_nop 0
	global_load_dwordx4 v[166:169], v[166:167], off offset:512
	ds_read_b128 v[170:173], v66
	ds_read_b128 v[174:177], v66 offset:32
	ds_read_b128 v[178:181], v65 offset:18432
	ds_read_b128 v[182:185], v65 offset:18464
	ds_read_b128 v[186:189], v65 offset:23040
	ds_read_b128 v[190:193], v65 offset:23072
	ds_read_b128 v[194:197], v65 offset:27648
	ds_read_b128 v[198:201], v65 offset:27680
	ds_read_b128 v[202:205], v65 offset:32256
	ds_read_b128 v[206:209], v65 offset:32288
	ds_read_b128 v[210:213], v66 offset:64
	ds_read_b128 v[214:217], v66 offset:96
	ds_read_b128 v[218:221], v65 offset:18496
	ds_read_b128 v[222:225], v65 offset:18528
	ds_read_b128 v[226:229], v65 offset:23104
	ds_read_b128 v[230:233], v65 offset:23136
	ds_read_b128 v[234:237], v65 offset:27712
	ds_read_b128 v[238:241], v65 offset:27744
	ds_read_b128 v[242:245], v65 offset:32320
	ds_read_b128 v[246:249], v65 offset:32352
	s_setprio 2
	s_waitcnt lgkmcnt(14)
	v_mfma_f32_32x32x16_bf16 v[48:63], v[170:173], v[178:181], v[48:63]
	v_mfma_f32_32x32x16_bf16 v[32:47], v[170:173], v[186:189], v[32:47]
	s_waitcnt lgkmcnt(13)
	v_mfma_f32_32x32x16_bf16 v[16:31], v[170:173], v[194:197], v[16:31]
	s_waitcnt lgkmcnt(11)
	v_mfma_f32_32x32x16_bf16 v[0:15], v[170:173], v[202:205], v[0:15]
	v_mfma_f32_32x32x16_bf16 v[48:63], v[174:177], v[182:185], v[48:63]
	v_mfma_f32_32x32x16_bf16 v[32:47], v[174:177], v[190:193], v[32:47]
	v_mfma_f32_32x32x16_bf16 v[16:31], v[174:177], v[198:201], v[16:31]
	s_waitcnt lgkmcnt(10)
	v_mfma_f32_32x32x16_bf16 v[0:15], v[174:177], v[206:209], v[0:15]
	s_waitcnt lgkmcnt(7)
	v_mfma_f32_32x32x16_bf16 v[48:63], v[210:213], v[218:221], v[48:63]
	s_waitcnt lgkmcnt(5)
	v_mfma_f32_32x32x16_bf16 v[32:47], v[210:213], v[226:229], v[32:47]
	s_waitcnt lgkmcnt(3)
	v_mfma_f32_32x32x16_bf16 v[16:31], v[210:213], v[234:237], v[16:31]
	s_waitcnt lgkmcnt(1)
	v_mfma_f32_32x32x16_bf16 v[0:15], v[210:213], v[242:245], v[0:15]
	v_mfma_f32_32x32x16_bf16 v[48:63], v[214:217], v[222:225], v[48:63]
	v_mfma_f32_32x32x16_bf16 v[32:47], v[214:217], v[230:233], v[32:47]
	v_mfma_f32_32x32x16_bf16 v[16:31], v[214:217], v[238:241], v[16:31]
	s_waitcnt lgkmcnt(0)
	v_mfma_f32_32x32x16_bf16 v[0:15], v[214:217], v[246:249], v[0:15]
	s_setprio 0
	s_cmp_gt_i32 s0, 0
	s_cselect_b32 s1, -1, 0
	s_cselect_b32 s0, 0xfffffd00, 0
	s_barrier
; #define MFMA(a, b, c) __builtin_amdgcn_mfma_f32_32x32x16_bf16((a), (b), (c), 0, 0, 0)
; DI void gt_compute(const bf16* asr, const bf16* bsr, f32x16& acc0, f32x16& acc1, f32x16& acc2, f32x16& acc3) {
;   bf16x8 a[4], b0[4], b1[4], b2[4], b3[4];
; #pragma unroll
;   for (int kk = 0; kk < 4; ++kk) {
;     a[kk] = *(const bf16x8*)(asr + kk * 16);
;     b0[kk] = *(const bf16x8*)(bsr + kk * 16);
;     b1[kk] = *(const bf16x8*)(bsr + 32 * LDT + kk * 16);
;     b2[kk] = *(const bf16x8*)(bsr + 64 * LDT + kk * 16);
;     b3[kk] = *(const bf16x8*)(bsr + 96 * LDT + kk * 16);
;   }
;   __builtin_amdgcn_sched_barrier(0);
;   __builtin_amdgcn_s_setprio(2);
; #pragma unroll
;   for (int kk = 0; kk < 4; ++kk) {
;     acc0 = MFMA(a[kk], b0[kk], acc0); acc1 = MFMA(a[kk], b1[kk], acc1); acc2 = MFMA(a[kk], b2[kk], acc2); acc3 = MFMA(a[kk], b3[kk], acc3);
;   }
;   __builtin_amdgcn_s_setprio(0);
;   __builtin_amdgcn_sched_barrier(0);
; DI void gemm_mainloop(const bf16* __restrict__ A, int lda, const bf16* __restrict__ Bt, int ldb, int K, int m0, int n0,
;                       bf16* As, bf16* Bs, f32x16& acc0, f32x16& acc1, f32x16& acc2, f32x16& acc3) {
;     ...
;   for (int k0 = 0; k0 < K; k0 += 128) {
;     __syncthreads();
;     gt_store(t0, asw, bsw);
;     __syncthreads();
;     if (k0 + 128 < K) gt_load(t0, ap, bp, lda, ldb, KW(k0 + 128));
;     gt_compute(asr, bsr, acc0, acc1, acc2, acc3);
;     __syncthreads();
;     gt_store(t1, asw, bsw);
;     __syncthreads();
;     if (k0 + 192 < K) gt_load(t1, ap, bp, lda, ldb, KW(k0 + 192));
;     gt_compute(asr, bsr, acc0, acc1, acc2, acc3);
	s_waitcnt vmcnt(13)
	ds_write_b128 v64, v[88:91]
	ds_write_b128 v64, v[80:83] offset:4608
	ds_write_b128 v64, v[84:87] offset:9216
	s_waitcnt vmcnt(11)
	ds_write_b128 v64, v[96:99] offset:13824
	ds_write_b128 v64, v[92:95] offset:18432
	s_waitcnt vmcnt(10)
	ds_write_b128 v64, v[100:103] offset:23040
	s_waitcnt vmcnt(9)
	ds_write_b128 v64, v[124:127] offset:27648
	s_waitcnt vmcnt(8)
	ds_write_b128 v64, v[130:133] offset:32256
	v_lshl_add_u64 v[84:85], v[76:77], 0, s[0:1]
	v_add_co_u32_e32 v76, vcc, s21, v84
	v_lshl_add_u64 v[100:101], v[78:79], 0, s[0:1]
	s_nop 0
	v_addc_co_u32_e32 v77, vcc, 0, v85, vcc
	v_add_co_u32_e32 v80, vcc, s28, v84
	s_waitcnt lgkmcnt(0)
	s_nop 0
	v_addc_co_u32_e32 v81, vcc, 0, v85, vcc
	v_add_co_u32_e32 v92, vcc, s29, v84
	s_barrier
	s_nop 0
	v_addc_co_u32_e32 v93, vcc, 0, v85, vcc
	v_add_co_u32_e32 v96, vcc, s34, v100
	s_nop 1
	v_addc_co_u32_e32 v97, vcc, 0, v101, vcc
	v_add_co_u32_e32 v102, vcc, s35, v100
	global_load_dwordx4 v[76:79], v[76:77], off offset:640
	s_nop 0
	global_load_dwordx4 v[80:83], v[80:81], off offset:640
	v_addc_co_u32_e32 v103, vcc, 0, v101, vcc
	v_add_co_u32_e32 v124, vcc, s38, v100
	global_load_dwordx4 v[84:87], v[84:85], off offset:640
	s_nop 0
	global_load_dwordx4 v[88:91], v[100:101], off offset:640
	v_addc_co_u32_e32 v125, vcc, 0, v101, vcc
	global_load_dwordx4 v[92:95], v[92:93], off offset:640
	s_nop 0
	global_load_dwordx4 v[96:99], v[96:97], off offset:640
	s_nop 0
	global_load_dwordx4 v[100:103], v[102:103], off offset:640
	s_nop 0
	global_load_dwordx4 v[124:127], v[124:125], off offset:640
	ds_read_b128 v[130:133], v66
	ds_read_b128 v[170:173], v66 offset:32
	ds_read_b128 v[174:177], v65 offset:18432
	ds_read_b128 v[178:181], v65 offset:18464
	ds_read_b128 v[182:185], v65 offset:23040
	ds_read_b128 v[186:189], v65 offset:23072
	ds_read_b128 v[190:193], v65 offset:27648
	ds_read_b128 v[194:197], v65 offset:27680
	ds_read_b128 v[198:201], v65 offset:32256
	ds_read_b128 v[202:205], v65 offset:32288
	ds_read_b128 v[206:209], v66 offset:64
	ds_read_b128 v[210:213], v66 offset:96
	ds_read_b128 v[214:217], v65 offset:18496
	ds_read_b128 v[218:221], v65 offset:18528
	ds_read_b128 v[222:225], v65 offset:23104
	ds_read_b128 v[226:229], v65 offset:23136
	ds_read_b128 v[230:233], v65 offset:27712
	ds_read_b128 v[234:237], v65 offset:27744
	ds_read_b128 v[238:241], v65 offset:32320
	ds_read_b128 v[242:245], v65 offset:32352
	s_setprio 2
	s_waitcnt lgkmcnt(14)
	v_mfma_f32_32x32x16_bf16 v[48:63], v[130:133], v[174:177], v[48:63]
	v_mfma_f32_32x32x16_bf16 v[32:47], v[130:133], v[182:185], v[32:47]
	s_waitcnt lgkmcnt(13)
	v_mfma_f32_32x32x16_bf16 v[16:31], v[130:133], v[190:193], v[16:31]
	s_waitcnt lgkmcnt(11)
	v_mfma_f32_32x32x16_bf16 v[0:15], v[130:133], v[198:201], v[0:15]
	v_mfma_f32_32x32x16_bf16 v[48:63], v[170:173], v[178:181], v[48:63]
	v_mfma_f32_32x32x16_bf16 v[32:47], v[170:173], v[186:189], v[32:47]
	v_mfma_f32_32x32x16_bf16 v[16:31], v[170:173], v[194:197], v[16:31]
	s_waitcnt lgkmcnt(10)
	v_mfma_f32_32x32x16_bf16 v[0:15], v[170:173], v[202:205], v[0:15]
	s_waitcnt lgkmcnt(7)
	v_mfma_f32_32x32x16_bf16 v[48:63], v[206:209], v[214:217], v[48:63]
	s_waitcnt lgkmcnt(5)
	v_mfma_f32_32x32x16_bf16 v[32:47], v[206:209], v[222:225], v[32:47]
	s_waitcnt lgkmcnt(3)
	v_mfma_f32_32x32x16_bf16 v[16:31], v[206:209], v[230:233], v[16:31]
	s_waitcnt lgkmcnt(1)
	v_mfma_f32_32x32x16_bf16 v[0:15], v[206:209], v[238:241], v[0:15]
	v_mfma_f32_32x32x16_bf16 v[48:63], v[210:213], v[218:221], v[48:63]
	v_mfma_f32_32x32x16_bf16 v[32:47], v[210:213], v[226:229], v[32:47]
	v_mfma_f32_32x32x16_bf16 v[16:31], v[210:213], v[234:237], v[16:31]
	s_waitcnt lgkmcnt(0)
	v_mfma_f32_32x32x16_bf16 v[0:15], v[210:213], v[242:245], v[0:15]
	s_setprio 0
	s_barrier
	s_waitcnt vmcnt(13)
	ds_write_b128 v64, v[142:145]
	ds_write_b128 v64, v[134:137] offset:4608
	ds_write_b128 v64, v[138:141] offset:9216
	s_waitcnt vmcnt(11)
	ds_write_b128 v64, v[150:153] offset:13824
	ds_write_b128 v64, v[146:149] offset:18432
	s_waitcnt vmcnt(10)
	ds_write_b128 v64, v[154:157] offset:23040
	s_waitcnt vmcnt(9)
	ds_write_b128 v64, v[162:165] offset:27648
	s_waitcnt vmcnt(8)
	ds_write_b128 v64, v[166:169] offset:32256
	s_waitcnt lgkmcnt(0)
	s_barrier
	ds_read_b128 v[130:133], v66
	ds_read_b128 v[134:137], v66 offset:32
	ds_read_b128 v[138:141], v65 offset:18432
	ds_read_b128 v[142:145], v65 offset:18464
	ds_read_b128 v[146:149], v65 offset:23040
	ds_read_b128 v[150:153], v65 offset:23072
	ds_read_b128 v[154:157], v65 offset:27648
	ds_read_b128 v[162:165], v65 offset:27680
	ds_read_b128 v[166:169], v65 offset:32256
	ds_read_b128 v[170:173], v65 offset:32288
	ds_read_b128 v[174:177], v66 offset:64
	ds_read_b128 v[178:181], v66 offset:96
	ds_read_b128 v[182:185], v65 offset:18496
	ds_read_b128 v[186:189], v65 offset:18528
	ds_read_b128 v[190:193], v65 offset:23104
	ds_read_b128 v[194:197], v65 offset:23136
	ds_read_b128 v[198:201], v65 offset:27712
	ds_read_b128 v[202:205], v65 offset:27744
	ds_read_b128 v[206:209], v65 offset:32320
	ds_read_b128 v[210:213], v65 offset:32352
	s_setprio 2
	s_waitcnt lgkmcnt(14)
	v_mfma_f32_32x32x16_bf16 v[48:63], v[130:133], v[138:141], v[48:63]
	v_mfma_f32_32x32x16_bf16 v[32:47], v[130:133], v[146:149], v[32:47]
	s_waitcnt lgkmcnt(13)
	v_mfma_f32_32x32x16_bf16 v[16:31], v[130:133], v[154:157], v[16:31]
	s_waitcnt lgkmcnt(11)
	v_mfma_f32_32x32x16_bf16 v[0:15], v[130:133], v[166:169], v[0:15]
	v_mfma_f32_32x32x16_bf16 v[48:63], v[134:137], v[142:145], v[48:63]
	v_mfma_f32_32x32x16_bf16 v[32:47], v[134:137], v[150:153], v[32:47]
	v_mfma_f32_32x32x16_bf16 v[16:31], v[134:137], v[162:165], v[16:31]
	s_waitcnt lgkmcnt(10)
	v_mfma_f32_32x32x16_bf16 v[0:15], v[134:137], v[170:173], v[0:15]
	s_waitcnt lgkmcnt(7)
	v_mfma_f32_32x32x16_bf16 v[48:63], v[174:177], v[182:185], v[48:63]
	s_waitcnt lgkmcnt(5)
	v_mfma_f32_32x32x16_bf16 v[32:47], v[174:177], v[190:193], v[32:47]
	s_waitcnt lgkmcnt(3)
	v_mfma_f32_32x32x16_bf16 v[16:31], v[174:177], v[198:201], v[16:31]
	s_waitcnt lgkmcnt(1)
	v_mfma_f32_32x32x16_bf16 v[0:15], v[174:177], v[206:209], v[0:15]
	v_mfma_f32_32x32x16_bf16 v[48:63], v[178:181], v[186:189], v[48:63]
	v_mfma_f32_32x32x16_bf16 v[32:47], v[178:181], v[194:197], v[32:47]
	v_mfma_f32_32x32x16_bf16 v[16:31], v[178:181], v[202:205], v[16:31]
	s_waitcnt lgkmcnt(0)
	v_mfma_f32_32x32x16_bf16 v[0:15], v[178:181], v[210:213], v[0:15]
	s_setprio 0
	s_barrier
; #define MFMA(a, b, c) __builtin_amdgcn_mfma_f32_32x32x16_bf16((a), (b), (c), 0, 0, 0)
; DI bf16 f2bf(float a) { return (bf16)(pack2(a, 0.f) & 0xffffu); }
; DI int crow(int i, int g) { return (i & 3) + 8 * (i >> 2) + 4 * g; }
; DI void gt_compute(const bf16* asr, const bf16* bsr, f32x16& acc0, f32x16& acc1, f32x16& acc2, f32x16& acc3) {
;   bf16x8 a[4], b0[4], b1[4], b2[4], b3[4];
; #pragma unroll
;   for (int kk = 0; kk < 4; ++kk) {
;     a[kk] = *(const bf16x8*)(asr + kk * 16);
;     b0[kk] = *(const bf16x8*)(bsr + kk * 16);
;     b1[kk] = *(const bf16x8*)(bsr + 32 * LDT + kk * 16);
;     b2[kk] = *(const bf16x8*)(bsr + 64 * LDT + kk * 16);
;     b3[kk] = *(const bf16x8*)(bsr + 96 * LDT + kk * 16);
;   }
;   __builtin_amdgcn_sched_barrier(0);
;   __builtin_amdgcn_s_setprio(2);
; #pragma unroll
;   for (int kk = 0; kk < 4; ++kk) {
;     acc0 = MFMA(a[kk], b0[kk], acc0); acc1 = MFMA(a[kk], b1[kk], acc1); acc2 = MFMA(a[kk], b2[kk], acc2); acc3 = MFMA(a[kk], b3[kk], acc3);
;   }
;   __builtin_amdgcn_s_setprio(0);
;   __builtin_amdgcn_sched_barrier(0);
; }
;     ...
;     } else if constexpr (EPI == EPI_MLA_Q) {
;       bf16* Qb = (bf16*)(ws + OFF_Q);
;       const float2* t64 = (const float2*)(ws + OFF_TAB64);
;       __syncthreads();
; #pragma unroll
;       for (int j = 0; j < 4; ++j) {
;         const int n = n0 + 32 * j;
;         const int hh = n / 192, d0 = n % 192;
;         if (d0 < 128) {
; #pragma unroll
;           for (int i = 0; i < 16; ++i) {
;             int rl = 32 * w + crow(i, g);
;             int s = (m0 & 2047) + rl;
;             Qb[((size_t)(bidx * 8 + hh) * 2048 + s) * 192 + d0 + r] = f2bf(acc[j][i] * rs[rl]);
;           }
;         } else if (d0 == 128) {
;           if (j < 3) {
; #pragma unroll
;             for (int i = 0; i < 16; ++i) {
;               int rl = 32 * w + crow(i, g);
;               int s = (m0 & 2047) + rl;
;               float2 cs = t64[s * 32 + r];
	s_waitcnt vmcnt(5)
	ds_write_b128 v64, v[84:87]
	ds_write_b128 v64, v[76:79] offset:4608
	ds_write_b128 v64, v[80:83] offset:9216
	s_waitcnt vmcnt(3)
	ds_write_b128 v64, v[92:95] offset:13824
	ds_write_b128 v64, v[88:91] offset:18432
	s_waitcnt vmcnt(2)
	ds_write_b128 v64, v[96:99] offset:23040
	s_waitcnt vmcnt(1)
	ds_write_b128 v64, v[100:103] offset:27648
	s_waitcnt vmcnt(0)
	ds_write_b128 v64, v[124:127] offset:32256
	s_waitcnt lgkmcnt(0)
	s_barrier
	ds_read_b128 v[76:79], v66
	ds_read_b128 v[80:83], v66 offset:32
	ds_read_b128 v[84:87], v65 offset:18432
	ds_read_b128 v[88:91], v65 offset:18464
	ds_read_b128 v[92:95], v65 offset:23040
	ds_read_b128 v[96:99], v65 offset:23072
	ds_read_b128 v[100:103], v65 offset:27648
	ds_read_b128 v[124:127], v65 offset:27680
	ds_read_b128 v[130:133], v65 offset:32256
	ds_read_b128 v[134:137], v65 offset:32288
	ds_read_b128 v[138:141], v66 offset:64
	ds_read_b128 v[142:145], v66 offset:96
	ds_read_b128 v[146:149], v65 offset:18496
	ds_read_b128 v[150:153], v65 offset:18528
	ds_read_b128 v[154:157], v65 offset:23104
	ds_read_b128 v[162:165], v65 offset:23136
	ds_read_b128 v[166:169], v65 offset:27712
	ds_read_b128 v[170:173], v65 offset:27744
	ds_read_b128 v[174:177], v65 offset:32320
	ds_read_b128 v[64:67], v65 offset:32352
	s_setprio 2
	s_waitcnt lgkmcnt(14)
	v_mfma_f32_32x32x16_bf16 v[48:63], v[76:79], v[84:87], v[48:63]
	v_mfma_f32_32x32x16_bf16 v[32:47], v[76:79], v[92:95], v[32:47]
	s_waitcnt lgkmcnt(13)
	v_mfma_f32_32x32x16_bf16 v[16:31], v[76:79], v[100:103], v[16:31]
	s_waitcnt lgkmcnt(11)
	v_mfma_f32_32x32x16_bf16 v[0:15], v[76:79], v[130:133], v[0:15]
	v_mfma_f32_32x32x16_bf16 v[48:63], v[80:83], v[88:91], v[48:63]
	v_mfma_f32_32x32x16_bf16 v[32:47], v[80:83], v[96:99], v[32:47]
	v_mfma_f32_32x32x16_bf16 v[16:31], v[80:83], v[124:127], v[16:31]
	s_waitcnt lgkmcnt(10)
	v_mfma_f32_32x32x16_bf16 v[0:15], v[80:83], v[134:137], v[0:15]
	s_waitcnt lgkmcnt(7)
	v_mfma_f32_32x32x16_bf16 v[48:63], v[138:141], v[146:149], v[48:63]
	s_waitcnt lgkmcnt(5)
	v_mfma_f32_32x32x16_bf16 v[32:47], v[138:141], v[154:157], v[32:47]
	s_waitcnt lgkmcnt(3)
	v_mfma_f32_32x32x16_bf16 v[16:31], v[138:141], v[166:169], v[16:31]
	s_waitcnt lgkmcnt(1)
	v_mfma_f32_32x32x16_bf16 v[0:15], v[138:141], v[174:177], v[0:15]
	v_mfma_f32_32x32x16_bf16 v[48:63], v[142:145], v[150:153], v[48:63]
	v_mfma_f32_32x32x16_bf16 v[32:47], v[142:145], v[162:165], v[32:47]
	v_mfma_f32_32x32x16_bf16 v[16:31], v[142:145], v[170:173], v[16:31]
	s_waitcnt lgkmcnt(0)
	v_mfma_f32_32x32x16_bf16 v[0:15], v[142:145], v[64:67], v[0:15]
	s_setprio 0
	s_ashr_i32 s0, s14, 1
	s_and_b32 s45, s0, -8
	s_mul_i32 s0, s12, 0x2aab
	s_lshr_b32 s1, s0, 31
	s_ashr_i32 s13, s0, 21
	s_add_i32 s13, s13, s1
	s_mul_i32 s0, s13, 0xc0
	s_sub_i32 s0, s12, s0
	s_and_b32 s46, s15, 0x780
	s_sext_i32_i16 s12, s0
	s_cmpk_gt_i32 s12, 0x7f
	s_mov_b64 s[14:15], -1
	s_barrier
	s_cbranch_scc0 .LBB0_329
	s_and_b32 s0, 0xffff, s0
	s_cmpk_lg_i32 s0, 0x80
	s_cbranch_scc1 .LBB0_328
	v_add_u32_e32 v80, s46, v107
	v_lshl_or_b32 v64, v80, 5, v105
	v_ashrrev_i32_e32 v65, 31, v64
	v_lshl_add_u64 v[64:65], v[64:65], 3, s[10:11]
	global_load_dwordx2 v[82:83], v[64:65], off
	v_add_u32_e32 v232, s46, v109
	v_lshl_or_b32 v232, v232, 5, v105
	v_mov_b32_e32 v233, 0
	v_lshl_add_u64 v[232:233], v[232:233], 3, s[10:11]
	global_load_dwordx2 v[202:203], v[232:233], off
	v_add_u32_e32 v234, s46, v110
	v_lshl_or_b32 v234, v234, 5, v105
	v_mov_b32_e32 v235, 0
	v_lshl_add_u64 v[234:235], v[234:235], 3, s[10:11]
	global_load_dwordx2 v[204:205], v[234:235], off
	v_add_u32_e32 v232, s46, v111
	v_lshl_or_b32 v232, v232, 5, v105
	v_mov_b32_e32 v233, 0
	v_lshl_add_u64 v[232:233], v[232:233], 3, s[10:11]
	global_load_dwordx2 v[206:207], v[232:233], off
	v_add_u32_e32 v234, s46, v112
	v_lshl_or_b32 v234, v234, 5, v105
	v_mov_b32_e32 v235, 0
	v_lshl_add_u64 v[234:235], v[234:235], 3, s[10:11]
	global_load_dwordx2 v[208:209], v[234:235], off
	v_add_u32_e32 v232, s46, v113
	v_lshl_or_b32 v232, v232, 5, v105
	v_mov_b32_e32 v233, 0
	v_lshl_add_u64 v[232:233], v[232:233], 3, s[10:11]
	global_load_dwordx2 v[210:211], v[232:233], off
	v_add_u32_e32 v234, s46, v114
	v_lshl_or_b32 v234, v234, 5, v105
	v_mov_b32_e32 v235, 0
	v_lshl_add_u64 v[234:235], v[234:235], 3, s[10:11]
	global_load_dwordx2 v[212:213], v[234:235], off
	v_add_u32_e32 v232, s46, v115
	v_lshl_or_b32 v232, v232, 5, v105
	v_mov_b32_e32 v233, 0
	v_lshl_add_u64 v[232:233], v[232:233], 3, s[10:11]
	global_load_dwordx2 v[214:215], v[232:233], off
	v_add_u32_e32 v234, s46, v116
	v_lshl_or_b32 v234, v234, 5, v105
	v_mov_b32_e32 v235, 0
	v_lshl_add_u64 v[234:235], v[234:235], 3, s[10:11]
	global_load_dwordx2 v[216:217], v[234:235], off
	v_add_u32_e32 v232, s46, v117
	v_lshl_or_b32 v232, v232, 5, v105
	v_mov_b32_e32 v233, 0
	v_lshl_add_u64 v[232:233], v[232:233], 3, s[10:11]
	global_load_dwordx2 v[218:219], v[232:233], off
	v_add_u32_e32 v234, s46, v118
	v_lshl_or_b32 v234, v234, 5, v105
	v_mov_b32_e32 v235, 0
	v_lshl_add_u64 v[234:235], v[234:235], 3, s[10:11]
	global_load_dwordx2 v[220:221], v[234:235], off
	v_add_u32_e32 v232, s46, v119
	v_lshl_or_b32 v232, v232, 5, v105
	v_mov_b32_e32 v233, 0
	v_lshl_add_u64 v[232:233], v[232:233], 3, s[10:11]
	global_load_dwordx2 v[222:223], v[232:233], off
	v_add_u32_e32 v234, s46, v120
	v_lshl_or_b32 v234, v234, 5, v105
	v_mov_b32_e32 v235, 0
	v_lshl_add_u64 v[234:235], v[234:235], 3, s[10:11]
	global_load_dwordx2 v[224:225], v[234:235], off
	v_add_u32_e32 v232, s46, v121
	v_lshl_or_b32 v232, v232, 5, v105
	v_mov_b32_e32 v233, 0
	v_lshl_add_u64 v[232:233], v[232:233], 3, s[10:11]
	global_load_dwordx2 v[226:227], v[232:233], off
	v_add_u32_e32 v234, s46, v122
	v_lshl_or_b32 v234, v234, 5, v105
	v_mov_b32_e32 v235, 0
	v_lshl_add_u64 v[234:235], v[234:235], 3, s[10:11]
	global_load_dwordx2 v[228:229], v[234:235], off
	v_add_u32_e32 v232, s46, v123
	v_lshl_or_b32 v232, v232, 5, v105
	v_mov_b32_e32 v233, 0
	v_lshl_add_u64 v[232:233], v[232:233], 3, s[10:11]
	global_load_dwordx2 v[230:231], v[232:233], off
	ds_read_b128 v[76:79], v108 offset:40960
	ds_read_b128 v[64:67], v108 offset:40992
	s_add_i32 s0, s45, s13
	s_ashr_i32 s1, s0, 31
	v_ashrrev_i32_e32 v81, 31, v80
	s_lshl_b64 s[14:15], s[0:1], 11
	v_lshl_add_u64 v[80:81], s[14:15], 0, v[80:81]
	s_waitcnt lgkmcnt(1)
; DI bf16 f2bf(float a) { return (bf16)(pack2(a, 0.f) & 0xffffu); }
; DI int crow(int i, int g) { return (i & 3) + 8 * (i >> 2) + 4 * g; }
;     ...
;         } else if (d0 == 128) {
;           if (j < 3) {
; #pragma unroll
;             for (int i = 0; i < 16; ++i) {
;               int rl = 32 * w + crow(i, g);
;               int s = (m0 & 2047) + rl;
;               float2 cs = t64[s * 32 + r];
;               float x1 = acc[j][i] * rs[rl], x2 = acc[(j + 1) & 3][i] * rs[rl];
;               bf16* qp = Qb + ((size_t)(bidx * 8 + hh) * 2048 + s) * 192 + 128;
;               qp[r] = f2bf(x1 * cs.x - x2 * cs.y);
;               qp[32 + r] = f2bf(x2 * cs.x + x1 * cs.y);
;             }
	v_mul_f32_e32 v68, v48, v76
	v_mul_f32_e32 v76, v32, v76
	v_add_u32_e32 v84, s46, v109
	v_mad_u64_u32 v[88:89], s[0:1], v80, s41, v[70:71]
	v_lshl_or_b32 v86, v84, 5, v105
	v_ashrrev_i32_e32 v87, 31, v86
	v_mad_i32_i24 v89, v81, s41, v89
	v_lshl_add_u64 v[86:87], v[86:87], 3, s[10:11]
	v_ashrrev_i32_e32 v85, 31, v84
	v_lshl_add_u64 v[84:85], s[14:15], 0, v[84:85]
	s_waitcnt vmcnt(0)
	v_mul_f32_e32 v80, v83, v76
	v_mul_f32_e32 v76, v82, v76
	v_fma_f32 v80, v82, v68, -v80
	v_fmac_f32_e32 v76, v83, v68
	v_cvt_pk_bf16_f32 v68, v80, s0
	v_cvt_pk_bf16_f32 v76, v76, s0
	global_store_short v[88:89], v68, off offset:256
	global_store_short v[88:89], v76, off offset:320
	v_mov_b32_e32 v80, v202
	v_mov_b32_e32 v81, v203
	v_mul_f32_e32 v68, v49, v77
	v_mul_f32_e32 v77, v33, v77
	v_add_u32_e32 v76, s46, v110
	v_mad_u64_u32 v[86:87], s[0:1], v84, s41, v[70:71]
	v_lshl_or_b32 v82, v76, 5, v105
	v_ashrrev_i32_e32 v83, 31, v82
	v_mad_i32_i24 v87, v85, s41, v87
	v_lshl_add_u64 v[82:83], v[82:83], 3, s[10:11]
	v_mul_f32_e32 v84, v81, v77
	v_mul_f32_e32 v77, v80, v77
	v_fma_f32 v80, v80, v68, -v84
	v_fmac_f32_e32 v77, v81, v68
	v_cvt_pk_bf16_f32 v68, v80, s0
	v_cvt_pk_bf16_f32 v77, v77, s0
	global_store_short v[86:87], v68, off offset:256
	global_store_short v[86:87], v77, off offset:320
	v_mov_b32_e32 v80, v204
	v_mov_b32_e32 v81, v205
	v_ashrrev_i32_e32 v77, 31, v76
	v_lshl_add_u64 v[76:77], s[14:15], 0, v[76:77]
	v_mad_u64_u32 v[86:87], s[0:1], v76, s41, v[70:71]
	v_mul_f32_e32 v76, v34, v78
	v_add_u32_e32 v82, s46, v111
	v_mul_f32_e32 v68, v50, v78
	v_mad_i32_i24 v87, v77, s41, v87
	v_lshl_or_b32 v84, v82, 5, v105
	v_ashrrev_i32_e32 v85, 31, v84
	v_lshl_add_u64 v[84:85], v[84:85], 3, s[10:11]
	v_ashrrev_i32_e32 v83, 31, v82
	v_lshl_add_u64 v[82:83], s[14:15], 0, v[82:83]
	v_add_u32_e32 v78, s46, v112
	v_mul_f32_e32 v77, v81, v76
	v_mul_f32_e32 v76, v80, v76
	v_fma_f32 v77, v80, v68, -v77
	v_fmac_f32_e32 v76, v81, v68
	v_cvt_pk_bf16_f32 v68, v77, s0
	v_cvt_pk_bf16_f32 v76, v76, s0
	global_store_short v[86:87], v68, off offset:256
	global_store_short v[86:87], v76, off offset:320
	v_mov_b32_e32 v76, v206
	v_mov_b32_e32 v77, v207
	v_mul_f32_e32 v68, v51, v79
	v_mul_f32_e32 v79, v35, v79
	v_mad_u64_u32 v[84:85], s[0:1], v82, s41, v[70:71]
	v_lshl_or_b32 v80, v78, 5, v105
	v_ashrrev_i32_e32 v81, 31, v80
	v_mad_i32_i24 v85, v83, s41, v85
	v_lshl_add_u64 v[80:81], v[80:81], 3, s[10:11]
	v_mul_f32_e32 v82, v77, v79
	v_mul_f32_e32 v79, v76, v79
	v_fma_f32 v76, v76, v68, -v82
	v_fmac_f32_e32 v79, v77, v68
	v_cvt_pk_bf16_f32 v68, v76, s0
	v_cvt_pk_bf16_f32 v76, v79, s0
	global_store_short v[84:85], v68, off offset:256
	global_store_short v[84:85], v76, off offset:320
	v_mov_b32_e32 v76, v208
	v_mov_b32_e32 v77, v209
	v_ashrrev_i32_e32 v79, 31, v78
	v_lshl_add_u64 v[78:79], s[14:15], 0, v[78:79]
	s_waitcnt lgkmcnt(0)
	v_mul_f32_e32 v68, v52, v64
	v_mul_f32_e32 v64, v36, v64
	v_add_u32_e32 v80, s46, v113
	v_mad_u64_u32 v[84:85], s[0:1], v78, s41, v[70:71]
	v_lshl_or_b32 v82, v80, 5, v105
	v_ashrrev_i32_e32 v83, 31, v82
	v_mad_i32_i24 v85, v79, s41, v85
	v_lshl_add_u64 v[82:83], v[82:83], 3, s[10:11]
	v_ashrrev_i32_e32 v81, 31, v80
	v_lshl_add_u64 v[80:81], s[14:15], 0, v[80:81]
	v_mul_f32_e32 v78, v77, v64
	v_mul_f32_e32 v64, v76, v64
	v_fma_f32 v76, v76, v68, -v78
	v_fmac_f32_e32 v64, v77, v68
	v_cvt_pk_bf16_f32 v68, v76, s0
	v_cvt_pk_bf16_f32 v64, v64, s0
	global_store_short v[84:85], v68, off offset:256
	global_store_short v[84:85], v64, off offset:320
	v_mov_b32_e32 v76, v210
	v_mov_b32_e32 v77, v211
	v_mul_f32_e32 v68, v53, v65
	v_mul_f32_e32 v65, v37, v65
	v_add_u32_e32 v64, s46, v114
	v_mad_u64_u32 v[82:83], s[0:1], v80, s41, v[70:71]
	v_lshl_or_b32 v78, v64, 5, v105
	v_ashrrev_i32_e32 v79, 31, v78
	v_mad_i32_i24 v83, v81, s41, v83
	v_lshl_add_u64 v[78:79], v[78:79], 3, s[10:11]
	v_add_u32_e32 v84, s46, v117
	v_lshl_or_b32 v86, v84, 5, v105
	v_ashrrev_i32_e32 v87, 31, v86
	v_lshl_add_u64 v[86:87], v[86:87], 3, s[10:11]
	v_ashrrev_i32_e32 v85, 31, v84
	v_lshl_add_u64 v[84:85], s[14:15], 0, v[84:85]
	v_mul_f32_e32 v80, v77, v65
	v_mul_f32_e32 v65, v76, v65
	v_fma_f32 v76, v76, v68, -v80
	v_fmac_f32_e32 v65, v77, v68
	v_cvt_pk_bf16_f32 v68, v76, s0
	v_cvt_pk_bf16_f32 v65, v65, s0
	global_store_short v[82:83], v68, off offset:256
	global_store_short v[82:83], v65, off offset:320
	v_mov_b32_e32 v76, v212
	v_mov_b32_e32 v77, v213
	v_ashrrev_i32_e32 v65, 31, v64
	v_lshl_add_u64 v[64:65], s[14:15], 0, v[64:65]
	v_mad_u64_u32 v[82:83], s[0:1], v64, s41, v[70:71]
	v_mul_f32_e32 v64, v54, v66
	v_mul_f32_e32 v66, v38, v66
	v_add_u32_e32 v78, s46, v115
	v_mad_i32_i24 v83, v65, s41, v83
	v_lshl_or_b32 v80, v78, 5, v105
	v_ashrrev_i32_e32 v81, 31, v80
	v_lshl_add_u64 v[80:81], v[80:81], 3, s[10:11]
	v_ashrrev_i32_e32 v79, 31, v78
	v_lshl_add_u64 v[78:79], s[14:15], 0, v[78:79]
	v_mul_f32_e32 v65, v77, v66
	v_mul_f32_e32 v66, v76, v66
	v_fma_f32 v65, v76, v64, -v65
	v_fmac_f32_e32 v66, v77, v64
	v_cvt_pk_bf16_f32 v64, v65, s0
	v_cvt_pk_bf16_f32 v65, v66, s0
	global_store_short v[82:83], v64, off offset:256
	global_store_short v[82:83], v65, off offset:320
	v_mov_b32_e32 v64, v214
	v_mov_b32_e32 v65, v215
	v_mul_f32_e32 v66, v55, v67
	v_mul_f32_e32 v67, v39, v67
	v_add_u32_e32 v80, s46, v116
	v_lshl_or_b32 v76, v80, 5, v105
	v_mad_u64_u32 v[82:83], s[0:1], v78, s41, v[70:71]
	v_ashrrev_i32_e32 v77, 31, v76
	v_mad_i32_i24 v83, v79, s41, v83
	v_lshl_add_u64 v[76:77], v[76:77], 3, s[10:11]
	v_ashrrev_i32_e32 v81, 31, v80
	v_lshl_add_u64 v[80:81], s[14:15], 0, v[80:81]
	v_mul_f32_e32 v68, v65, v67
	v_mul_f32_e32 v67, v64, v67
	v_fma_f32 v64, v64, v66, -v68
	v_fmac_f32_e32 v67, v65, v66
	v_cvt_pk_bf16_f32 v64, v64, s0
	v_cvt_pk_bf16_f32 v65, v67, s0
	global_store_short v[82:83], v64, off offset:256
	global_store_short v[82:83], v65, off offset:320
	v_mov_b32_e32 v82, v216
	v_mov_b32_e32 v83, v217
	ds_read_b128 v[64:67], v108 offset:41024
	ds_read_b128 v[76:79], v108 offset:41056
	v_mad_u64_u32 v[88:89], s[0:1], v80, s41, v[70:71]
	v_mad_i32_i24 v89, v81, s41, v89
	s_waitcnt lgkmcnt(1)
; DI bf16 f2bf(float a) { return (bf16)(pack2(a, 0.f) & 0xffffu); }
; DI int crow(int i, int g) { return (i & 3) + 8 * (i >> 2) + 4 * g; }
;     ...
;         } else if (d0 == 128) {
;           if (j < 3) {
; #pragma unroll
;             for (int i = 0; i < 16; ++i) {
;               int rl = 32 * w + crow(i, g);
;               int s = (m0 & 2047) + rl;
;               float2 cs = t64[s * 32 + r];
;               float x1 = acc[j][i] * rs[rl], x2 = acc[(j + 1) & 3][i] * rs[rl];
;               bf16* qp = Qb + ((size_t)(bidx * 8 + hh) * 2048 + s) * 192 + 128;
;               qp[r] = f2bf(x1 * cs.x - x2 * cs.y);
;               qp[32 + r] = f2bf(x2 * cs.x + x1 * cs.y);
;             }
	v_mul_f32_e32 v68, v56, v64
	v_mul_f32_e32 v64, v40, v64
	v_mul_f32_e32 v80, v83, v64
	v_mul_f32_e32 v64, v82, v64
	v_fma_f32 v80, v82, v68, -v80
	v_fmac_f32_e32 v64, v83, v68
	v_cvt_pk_bf16_f32 v68, v80, s0
	v_cvt_pk_bf16_f32 v64, v64, s0
	global_store_short v[88:89], v68, off offset:256
	global_store_short v[88:89], v64, off offset:320
	v_mov_b32_e32 v80, v218
	v_mov_b32_e32 v81, v219
	v_mul_f32_e32 v68, v57, v65
	v_mul_f32_e32 v65, v41, v65
	v_add_u32_e32 v64, s46, v118
	v_mad_u64_u32 v[86:87], s[0:1], v84, s41, v[70:71]
	v_lshl_or_b32 v82, v64, 5, v105
	v_ashrrev_i32_e32 v83, 31, v82
	v_mad_i32_i24 v87, v85, s41, v87
	v_lshl_add_u64 v[82:83], v[82:83], 3, s[10:11]
	v_mul_f32_e32 v84, v81, v65
	v_mul_f32_e32 v65, v80, v65
	v_fma_f32 v80, v80, v68, -v84
	v_fmac_f32_e32 v65, v81, v68
	v_cvt_pk_bf16_f32 v68, v80, s0
	v_cvt_pk_bf16_f32 v65, v65, s0
	global_store_short v[86:87], v68, off offset:256
	global_store_short v[86:87], v65, off offset:320
	v_mov_b32_e32 v80, v220
	v_mov_b32_e32 v81, v221
	v_ashrrev_i32_e32 v65, 31, v64
	v_lshl_add_u64 v[64:65], s[14:15], 0, v[64:65]
	v_mad_u64_u32 v[86:87], s[0:1], v64, s41, v[70:71]
	v_mul_f32_e32 v64, v58, v66
	v_mul_f32_e32 v66, v42, v66
	v_add_u32_e32 v82, s46, v119
	v_mad_i32_i24 v87, v65, s41, v87
	v_lshl_or_b32 v84, v82, 5, v105
	v_ashrrev_i32_e32 v85, 31, v84
	v_lshl_add_u64 v[84:85], v[84:85], 3, s[10:11]
	v_ashrrev_i32_e32 v83, 31, v82
	v_lshl_add_u64 v[82:83], s[14:15], 0, v[82:83]
	v_mul_f32_e32 v68, v59, v67
	v_mul_f32_e32 v67, v43, v67
	v_mul_f32_e32 v65, v81, v66
	v_mul_f32_e32 v66, v80, v66
	v_fma_f32 v65, v80, v64, -v65
	v_fmac_f32_e32 v66, v81, v64
	v_cvt_pk_bf16_f32 v64, v65, s0
	v_cvt_pk_bf16_f32 v65, v66, s0
	global_store_short v[86:87], v64, off offset:256
	global_store_short v[86:87], v65, off offset:320
	v_mov_b32_e32 v64, v222
	v_mov_b32_e32 v65, v223
	v_add_u32_e32 v66, s46, v120
	v_mad_u64_u32 v[84:85], s[0:1], v82, s41, v[70:71]
	v_lshl_or_b32 v80, v66, 5, v105
	v_ashrrev_i32_e32 v81, 31, v80
	v_mad_i32_i24 v85, v83, s41, v85
	v_lshl_add_u64 v[80:81], v[80:81], 3, s[10:11]
	v_mul_f32_e32 v82, v65, v67
	v_mul_f32_e32 v67, v64, v67
	v_fma_f32 v64, v64, v68, -v82
	v_fmac_f32_e32 v67, v65, v68
	v_cvt_pk_bf16_f32 v64, v64, s0
	v_cvt_pk_bf16_f32 v65, v67, s0
	global_store_short v[84:85], v64, off offset:256
	global_store_short v[84:85], v65, off offset:320
	v_mov_b32_e32 v64, v224
	v_mov_b32_e32 v65, v225
	v_ashrrev_i32_e32 v67, 31, v66
	v_lshl_add_u64 v[66:67], s[14:15], 0, v[66:67]
	v_mad_u64_u32 v[84:85], s[0:1], v66, s41, v[70:71]
	s_waitcnt lgkmcnt(0)
	v_mul_f32_e32 v68, v44, v76
	v_add_u32_e32 v80, s46, v121
	v_mul_f32_e32 v66, v60, v76
	v_mad_i32_i24 v85, v67, s41, v85
	v_lshl_or_b32 v82, v80, 5, v105
	v_ashrrev_i32_e32 v83, 31, v82
	v_lshl_add_u64 v[82:83], v[82:83], 3, s[10:11]
	v_ashrrev_i32_e32 v81, 31, v80
	v_lshl_add_u64 v[80:81], s[14:15], 0, v[80:81]
	v_mul_f32_e32 v67, v65, v68
	v_mul_f32_e32 v68, v64, v68
	v_fma_f32 v64, v64, v66, -v67
	v_fmac_f32_e32 v68, v65, v66
	v_cvt_pk_bf16_f32 v64, v64, s0
	v_cvt_pk_bf16_f32 v65, v68, s0
	global_store_short v[84:85], v64, off offset:256
	global_store_short v[84:85], v65, off offset:320
	v_mov_b32_e32 v64, v226
	v_mov_b32_e32 v65, v227
	v_mul_f32_e32 v68, v45, v77
	v_add_u32_e32 v66, s46, v122
	v_mul_f32_e32 v67, v61, v77
	v_lshl_or_b32 v82, v66, 5, v105
	v_mad_u64_u32 v[84:85], s[0:1], v80, s41, v[70:71]
	v_ashrrev_i32_e32 v83, 31, v82
	v_mad_i32_i24 v85, v81, s41, v85
	v_lshl_add_u64 v[82:83], v[82:83], 3, s[10:11]
	v_mul_f32_e32 v76, v65, v68
	v_mul_f32_e32 v68, v64, v68
	v_fma_f32 v64, v64, v67, -v76
	v_fmac_f32_e32 v68, v65, v67
	v_cvt_pk_bf16_f32 v64, v64, s0
	v_cvt_pk_bf16_f32 v65, v68, s0
	global_store_short v[84:85], v64, off offset:256
	global_store_short v[84:85], v65, off offset:320
	v_mov_b32_e32 v64, v228
	v_mov_b32_e32 v65, v229
	v_ashrrev_i32_e32 v67, 31, v66
	v_lshl_add_u64 v[66:67], s[14:15], 0, v[66:67]
	v_mad_u64_u32 v[82:83], s[0:1], v66, s41, v[70:71]
	v_mul_f32_e32 v68, v46, v78
	v_add_u32_e32 v76, s46, v123
	v_mul_f32_e32 v66, v62, v78
	v_mad_i32_i24 v83, v67, s41, v83
	v_lshl_or_b32 v80, v76, 5, v105
	v_ashrrev_i32_e32 v81, 31, v80
	v_lshl_add_u64 v[80:81], v[80:81], 3, s[10:11]
	v_ashrrev_i32_e32 v77, 31, v76
	v_mul_f32_e32 v67, v65, v68
	v_mul_f32_e32 v68, v64, v68
	v_fma_f32 v64, v64, v66, -v67
	v_fmac_f32_e32 v68, v65, v66
	v_cvt_pk_bf16_f32 v64, v64, s0
	v_cvt_pk_bf16_f32 v65, v68, s0
	global_store_short v[82:83], v64, off offset:256
	global_store_short v[82:83], v65, off offset:320
	v_mov_b32_e32 v64, v230
	v_mov_b32_e32 v65, v231
	v_lshl_add_u64 v[66:67], s[14:15], 0, v[76:77]
	v_mad_u64_u32 v[76:77], s[0:1], v66, s41, v[70:71]
	v_mul_f32_e32 v68, v47, v79
	v_mul_f32_e32 v66, v63, v79
	v_mad_i32_i24 v77, v67, s41, v77
	v_mul_f32_e32 v67, v65, v68
	v_mul_f32_e32 v68, v64, v68
	v_fma_f32 v64, v64, v66, -v67
	v_fmac_f32_e32 v68, v65, v66
	v_cvt_pk_bf16_f32 v64, v64, s0
	v_cvt_pk_bf16_f32 v65, v68, s0
	global_store_short v[76:77], v64, off offset:256
	global_store_short v[76:77], v65, off offset:320

; DI int opaque_tid() { int t = threadIdx.x; asm volatile("" : "+v"(t)); return t; }
; DI void gemm_mainloop(const bf16* __restrict__ A, int lda, const bf16* __restrict__ Bt, int ldb, int K, int m0, int n0,
;                       bf16* As, bf16* Bs, f32x16& acc0, f32x16& acc1, f32x16& acc2, f32x16& acc3) {
;   const int tid = opaque_tid(), lane = tid & 63, w = tid >> 6, r = lane & 31, g = lane >> 5;
;   const int lrow = tid >> 3, lcc = (tid & 7) * 8;
;   const bf16* ap = A + (size_t)(m0 + lrow) * lda + lcc;
;   const bf16* bp = Bt + (size_t)(n0 + lrow) * ldb + lcc;
;   GTile t0, t1;
;   asm volatile("" ::: "memory");
;   const int nkt = K >> 6;
;   int kb = ((((m0 >> 7) * 5 + (n0 >> 7) * 3) >> 1) % nkt) << 6;
;     ...
;   gt_load(t0, ap, bp, lda, ldb, KW(0));
;   gt_load(t1, ap, bp, lda, ldb, KW(64));
;     ...
;     if (EPI == EPI_MLA_Q || EPI == EPI_MLA_KV) {
;       __syncthreads();
;       if (tid < 128) {
;         const float* rp = (const float*)(ws + OFF_RSS) + (size_t)(m0 + tid) * 8;
;         const float ssq = (EPI == EPI_MLA_Q) ? ((rp[0] + rp[1]) + rp[2]) : (rp[3] + rp[4]);
;         rs[tid] = rsqrtf(ssq / (float)K + 1e-6f);
;       }
;     }
.LBB0_344:
	s_ashr_i32 s0, s47, 31
	s_lshr_b32 s0, s0, 28
	s_add_i32 s0, s47, s0
	s_ashr_i32 s28, s0, 4
	s_lshl_b32 s0, s28, 7
	s_barrier
	s_and_saveexec_b64 s[18:19], s[6:7]
	s_cbranch_execz .LBB0_346
	v_add_u32_e32 v246, s0, v100
	v_ashrrev_i32_e32 v247, 31, v246
	v_lshlrev_b64 v[246:247], 5, v[246:247]
	v_lshl_add_u64 v[246:247], s[22:23], 0, v[246:247]
	v_add_co_u32_e32 v246, vcc, 0x1cc00000, v246
	s_nop 1
	v_addc_co_u32_e32 v247, vcc, 0, v247, vcc
	global_load_dwordx2 v[246:247], v[246:247], off offset:12
.LBB0_346:
	s_or_b64 exec, exec, s[18:19]
	v_mov_b32_e32 v40, v160
	s_lshl_b32 s1, s28, 11
	v_ashrrev_i32_e32 v41, 3, v40
	v_lshlrev_b32_e32 v2, 4, v40
	v_and_b32_e32 v72, 0x70, v2
	v_subrev_u32_e32 v2, s1, v41
	s_mul_i32 s1, s28, 0xffffffd5
	v_add_u32_e32 v0, s0, v41
	s_add_i32 s1, s30, s1
	v_mad_i64_i32 v[0:1], s[18:19], v0, s35, v[78:79]
	s_ashr_i32 s1, s1, 1
	s_lshr_b32 s18, s1, 30
	s_add_i32 s18, s1, s18
	s_and_b32 s18, s18, -4
	s_sub_i32 s18, s1, s18
	s_lshl_b32 s48, s18, 6
	s_ashr_i32 s49, s48, 31
	v_lshl_add_u64 v[0:1], v[0:1], 0, v[72:73]
	s_lshl_b64 s[48:49], s[48:49], 1
	s_waitcnt vmcnt(0)
	v_lshl_add_u64 v[126:127], v[0:1], 0, s[48:49]
	v_add_u32_e32 v2, s4, v2
	v_add_co_u32_e32 v0, vcc, s38, v126
	v_ashrrev_i32_e32 v3, 31, v2
	s_nop 0
	v_addc_co_u32_e32 v1, vcc, 0, v127, vcc
	v_lshlrev_b64 v[2:3], 9, v[2:3]
	v_add_co_u32_e32 v4, vcc, s39, v126
	v_lshl_add_u64 v[2:3], s[8:9], 0, v[2:3]
	s_nop 0
	v_addc_co_u32_e32 v5, vcc, 0, v127, vcc
	v_lshl_add_u64 v[2:3], v[2:3], 0, v[72:73]
	v_add_co_u32_e32 v16, vcc, s40, v126
	v_lshl_add_u64 v[128:129], v[2:3], 0, s[48:49]
	s_nop 0
	v_addc_co_u32_e32 v17, vcc, 0, v127, vcc
	v_add_co_u32_e32 v20, vcc, s41, v128
	global_load_dwordx4 v[0:3], v[0:1], off
	s_nop 0
	global_load_dwordx4 v[4:7], v[4:5], off
	v_addc_co_u32_e32 v21, vcc, 0, v129, vcc
	v_add_co_u32_e32 v24, vcc, s42, v128
	global_load_dwordx4 v[8:11], v[126:127], off
	global_load_dwordx4 v[12:15], v[128:129], off
	v_addc_co_u32_e32 v25, vcc, 0, v129, vcc
	v_add_co_u32_e32 v28, vcc, s43, v128
	global_load_dwordx4 v[16:19], v[16:17], off
	s_nop 0
	global_load_dwordx4 v[20:23], v[20:21], off
	v_addc_co_u32_e32 v29, vcc, 0, v129, vcc
	global_load_dwordx4 v[24:27], v[24:25], off
	s_nop 0
	global_load_dwordx4 v[28:31], v[28:29], off
	s_lshl_b32 s1, s28, 4
	s_sub_i32 s1, s47, s1
	s_cmp_lt_i32 s18, 3
	s_cselect_b32 s49, 0, -1
	s_cselect_b32 s48, 0, 0xfffffe00
	v_lshl_add_u64 v[32:33], v[126:127], 0, s[48:49]
	v_add_co_u32_e32 v36, vcc, s38, v32
	v_lshl_add_u64 v[34:35], v[128:129], 0, s[48:49]
	s_nop 0
	v_addc_co_u32_e32 v37, vcc, 0, v33, vcc
	v_add_co_u32_e32 v38, vcc, s39, v32
	v_mad_u64_u32 v[64:65], s[48:49], v41, s44, v[72:73]
	s_nop 0
	v_addc_co_u32_e32 v39, vcc, 0, v33, vcc
	global_load_dwordx4 v[68:71], v[36:37], off offset:128
	global_load_dwordx4 v[88:91], v[38:39], off offset:128
	v_add_co_u32_e32 v36, vcc, s40, v32
	global_load_dwordx4 v[92:95], v[32:33], off offset:128
	global_load_dwordx4 v[96:99], v[34:35], off offset:128
	v_addc_co_u32_e32 v37, vcc, 0, v33, vcc
	v_add_co_u32_e32 v32, vcc, s41, v34
	s_cmp_lt_i32 s18, 2
	s_nop 0
	v_addc_co_u32_e32 v33, vcc, 0, v35, vcc
	global_load_dwordx4 v[122:125], v[36:37], off offset:128
	global_load_dwordx4 v[130:133], v[32:33], off offset:128
	v_add_co_u32_e32 v32, vcc, s42, v34
	s_cselect_b32 s49, 0, -1
	s_nop 0
	v_addc_co_u32_e32 v33, vcc, 0, v35, vcc
	v_add_co_u32_e32 v34, vcc, s43, v34
	s_cselect_b32 s48, 0, 0xfffffe00
	s_nop 0
	v_addc_co_u32_e32 v35, vcc, 0, v35, vcc
	global_load_dwordx4 v[134:137], v[32:33], off offset:128
	global_load_dwordx4 v[138:141], v[34:35], off offset:128
	s_movk_i32 s100, 0x80
	v_cmp_gt_u32_e64 s[100:101], s100, v160
	s_and_saveexec_b64 s[98:99], s[100:101]
	s_cbranch_execz .Lmy_rss_kv
	s_waitcnt vmcnt(16)
	v_add_f32_e32 v246, v246, v247
	v_fmamk_f32 v246, v246, 0x3b800000, v120
	v_mul_f32_e32 v247, 0x4b800000, v246
	v_cmp_gt_f32_e32 vcc, s34, v246
	s_nop 1
	v_cndmask_b32_e32 v246, v246, v247, vcc
	v_rsq_f32_e32 v246, v246
	s_nop 0
	v_mul_f32_e32 v247, 0x45800000, v246
	v_cndmask_b32_e32 v246, v246, v247, vcc
	ds_write_b32 v101, v246 offset:40960
.Lmy_rss_kv:
	s_or_b64 exec, exec, s[98:99]
	s_waitcnt lgkmcnt(0)
	s_barrier
	s_waitcnt vmcnt(13)
	ds_write_b128 v64, v[8:11]
	ds_write_b128 v64, v[0:3] offset:4608
	ds_write_b128 v64, v[4:7] offset:9216
	s_waitcnt vmcnt(11)
	ds_write_b128 v64, v[16:19] offset:13824
	ds_write_b128 v64, v[12:15] offset:18432
	s_waitcnt vmcnt(10)
	ds_write_b128 v64, v[20:23] offset:23040
	s_waitcnt vmcnt(9)
	ds_write_b128 v64, v[24:27] offset:27648
	s_waitcnt vmcnt(8)
	ds_write_b128 v64, v[28:31] offset:32256
	v_lshl_add_u64 v[0:1], v[126:127], 0, s[48:49]
	v_add_co_u32_e32 v4, vcc, s38, v0
	s_waitcnt lgkmcnt(0)
	s_nop 0
	v_addc_co_u32_e32 v5, vcc, 0, v1, vcc
	v_add_co_u32_e32 v6, vcc, s39, v0
	s_barrier
; #define MFMA(a, b, c) __builtin_amdgcn_mfma_f32_32x32x16_bf16((a), (b), (c), 0, 0, 0)
; DI void gt_compute(const bf16* asr, const bf16* bsr, f32x16& acc0, f32x16& acc1, f32x16& acc2, f32x16& acc3) {
;   bf16x8 a[4], b0[4], b1[4], b2[4], b3[4];
; #pragma unroll
;   for (int kk = 0; kk < 4; ++kk) {
;     a[kk] = *(const bf16x8*)(asr + kk * 16);
;     b0[kk] = *(const bf16x8*)(bsr + kk * 16);
;     b1[kk] = *(const bf16x8*)(bsr + 32 * LDT + kk * 16);
;     b2[kk] = *(const bf16x8*)(bsr + 64 * LDT + kk * 16);
;     b3[kk] = *(const bf16x8*)(bsr + 96 * LDT + kk * 16);
;   }
;   __builtin_amdgcn_sched_barrier(0);
;   __builtin_amdgcn_s_setprio(2);
; #pragma unroll
;   for (int kk = 0; kk < 4; ++kk) {
;     acc0 = MFMA(a[kk], b0[kk], acc0); acc1 = MFMA(a[kk], b1[kk], acc1); acc2 = MFMA(a[kk], b2[kk], acc2); acc3 = MFMA(a[kk], b3[kk], acc3);
;   }
;   __builtin_amdgcn_s_setprio(0);
;   __builtin_amdgcn_sched_barrier(0);
; }
; DI void gemm_mainloop(const bf16* __restrict__ A, int lda, const bf16* __restrict__ Bt, int ldb, int K, int m0, int n0,
;                       bf16* As, bf16* Bs, f32x16& acc0, f32x16& acc1, f32x16& acc2, f32x16& acc3) {
;   const int tid = opaque_tid(), lane = tid & 63, w = tid >> 6, r = lane & 31, g = lane >> 5;
;   const int lrow = tid >> 3, lcc = (tid & 7) * 8;
;   const bf16* ap = A + (size_t)(m0 + lrow) * lda + lcc;
;   const bf16* bp = Bt + (size_t)(n0 + lrow) * ldb + lcc;
;   GTile t0, t1;
;   asm volatile("" ::: "memory");
;   const int nkt = K >> 6;
;   int kb = ((((m0 >> 7) * 5 + (n0 >> 7) * 3) >> 1) % nkt) << 6;
;     ...
;   gt_load(t0, ap, bp, lda, ldb, KW(0));
;   gt_load(t1, ap, bp, lda, ldb, KW(64));
; #pragma unroll
;   for (int i = 0; i < 16; ++i) { acc0[i] = 0.f; acc1[i] = 0.f; acc2[i] = 0.f; acc3[i] = 0.f; }
;   bf16* asw = As + lrow * LDT + lcc;
;   bf16* bsw = Bs + lrow * LDT + lcc;
;   const bf16* asr = As + (32 * w + r) * LDT + g * 8;
;   const bf16* bsr = Bs + r * LDT + g * 8;
;   for (int k0 = 0; k0 < K; k0 += 128) {
;     __syncthreads();
;     gt_store(t0, asw, bsw);
;     __syncthreads();
;     if (k0 + 128 < K) gt_load(t0, ap, bp, lda, ldb, KW(k0 + 128));
;     gt_compute(asr, bsr, acc0, acc1, acc2, acc3);
;     __syncthreads();
;     gt_store(t1, asw, bsw);
;     __syncthreads();
;     if (k0 + 192 < K) gt_load(t1, ap, bp, lda, ldb, KW(k0 + 192));
;     gt_compute(asr, bsr, acc0, acc1, acc2, acc3);
	s_nop 0
	v_addc_co_u32_e32 v7, vcc, 0, v1, vcc
	global_load_dwordx4 v[142:145], v[4:5], off offset:256
	global_load_dwordx4 v[146:149], v[6:7], off offset:256
	v_add_co_u32_e32 v4, vcc, s40, v0
	v_lshl_add_u64 v[2:3], v[128:129], 0, s[48:49]
	s_nop 0
	v_addc_co_u32_e32 v5, vcc, 0, v1, vcc
	global_load_dwordx4 v[150:153], v[0:1], off offset:256
	global_load_dwordx4 v[154:157], v[2:3], off offset:256
	v_add_co_u32_e32 v0, vcc, s41, v2
	s_nop 1
	v_addc_co_u32_e32 v1, vcc, 0, v3, vcc
	global_load_dwordx4 v[162:165], v[4:5], off offset:256
	global_load_dwordx4 v[166:169], v[0:1], off offset:256
	v_add_co_u32_e32 v0, vcc, s42, v2
	s_nop 1
	v_addc_co_u32_e32 v1, vcc, 0, v3, vcc
	v_add_co_u32_e32 v2, vcc, s43, v2
	s_nop 1
	v_addc_co_u32_e32 v3, vcc, 0, v3, vcc
	global_load_dwordx4 v[170:173], v[0:1], off offset:256
	global_load_dwordx4 v[174:177], v[2:3], off offset:256
	v_and_b32_e32 v1, 31, v40
	v_lshrrev_b32_e32 v0, 1, v40
	v_and_or_b32 v2, v0, s45, v1
	v_and_b32_e32 v0, 16, v0
	v_mad_u64_u32 v[66:67], s[48:49], v2, s44, v[0:1]
	v_mad_u32_u24 v72, v1, s44, v0
	ds_read_b128 v[0:3], v66
	ds_read_b128 v[178:181], v66 offset:32
	ds_read_b128 v[4:7], v72 offset:18432
	ds_read_b128 v[182:185], v72 offset:18464
	ds_read_b128 v[8:11], v72 offset:23040
	ds_read_b128 v[186:189], v72 offset:23072
	ds_read_b128 v[12:15], v72 offset:27648
	ds_read_b128 v[190:193], v72 offset:27680
	ds_read_b128 v[194:197], v72 offset:32256
	ds_read_b128 v[198:201], v72 offset:32288
	ds_read_b128 v[202:205], v66 offset:64
	ds_read_b128 v[206:209], v66 offset:96
	ds_read_b128 v[210:213], v72 offset:18496
	ds_read_b128 v[214:217], v72 offset:18528
	ds_read_b128 v[218:221], v72 offset:23104
	ds_read_b128 v[222:225], v72 offset:23136
	ds_read_b128 v[226:229], v72 offset:27712
	ds_read_b128 v[230:233], v72 offset:27744
	ds_read_b128 v[234:237], v72 offset:32320
	ds_read_b128 v[238:241], v72 offset:32352
	s_setprio 2
	s_waitcnt lgkmcnt(14)
	v_mfma_f32_32x32x16_bf16 v[48:63], v[0:3], v[4:7], 0
	v_mfma_f32_32x32x16_bf16 v[32:47], v[0:3], v[8:11], 0
	s_waitcnt lgkmcnt(13)
	v_mfma_f32_32x32x16_bf16 v[16:31], v[0:3], v[12:15], 0
	s_waitcnt lgkmcnt(11)
	v_mfma_f32_32x32x16_bf16 v[0:15], v[0:3], v[194:197], 0
	v_mfma_f32_32x32x16_bf16 v[48:63], v[178:181], v[182:185], v[48:63]
	v_mfma_f32_32x32x16_bf16 v[32:47], v[178:181], v[186:189], v[32:47]
	v_mfma_f32_32x32x16_bf16 v[16:31], v[178:181], v[190:193], v[16:31]
	s_waitcnt lgkmcnt(10)
	v_mfma_f32_32x32x16_bf16 v[0:15], v[178:181], v[198:201], v[0:15]
	s_waitcnt lgkmcnt(7)
	v_mfma_f32_32x32x16_bf16 v[48:63], v[202:205], v[210:213], v[48:63]
	s_waitcnt lgkmcnt(5)
	v_mfma_f32_32x32x16_bf16 v[32:47], v[202:205], v[218:221], v[32:47]
	s_waitcnt lgkmcnt(3)
	v_mfma_f32_32x32x16_bf16 v[16:31], v[202:205], v[226:229], v[16:31]
	s_waitcnt lgkmcnt(1)
	v_mfma_f32_32x32x16_bf16 v[0:15], v[202:205], v[234:237], v[0:15]
	v_mfma_f32_32x32x16_bf16 v[48:63], v[206:209], v[214:217], v[48:63]
	v_mfma_f32_32x32x16_bf16 v[32:47], v[206:209], v[222:225], v[32:47]
	v_mfma_f32_32x32x16_bf16 v[16:31], v[206:209], v[230:233], v[16:31]
	s_waitcnt lgkmcnt(0)
	v_mfma_f32_32x32x16_bf16 v[0:15], v[206:209], v[238:241], v[0:15]
	s_setprio 0
	s_cmp_gt_i32 s18, 0
	s_cselect_b32 s19, -1, 0
	s_cselect_b32 s18, 0xfffffe00, 0
	s_barrier
	s_waitcnt vmcnt(13)
	ds_write_b128 v64, v[92:95]
	ds_write_b128 v64, v[68:71] offset:4608
	ds_write_b128 v64, v[88:91] offset:9216
	s_waitcnt vmcnt(11)
	ds_write_b128 v64, v[122:125] offset:13824
	ds_write_b128 v64, v[96:99] offset:18432
	s_waitcnt vmcnt(10)
	ds_write_b128 v64, v[130:133] offset:23040
	s_waitcnt vmcnt(9)
	ds_write_b128 v64, v[134:137] offset:27648
	s_waitcnt vmcnt(8)
	ds_write_b128 v64, v[138:141] offset:32256
	v_lshl_add_u64 v[92:93], v[126:127], 0, s[18:19]
	v_add_co_u32_e32 v68, vcc, s38, v92
	v_lshl_add_u64 v[126:127], v[128:129], 0, s[18:19]
	s_nop 0
	v_addc_co_u32_e32 v69, vcc, 0, v93, vcc
	v_add_co_u32_e32 v88, vcc, s39, v92
	s_waitcnt lgkmcnt(0)
	s_nop 0
	v_addc_co_u32_e32 v89, vcc, 0, v93, vcc
	v_add_co_u32_e32 v122, vcc, s40, v92
	s_barrier
	s_nop 0
	v_addc_co_u32_e32 v123, vcc, 0, v93, vcc
	v_add_co_u32_e32 v128, vcc, s41, v126
	s_nop 1
	v_addc_co_u32_e32 v129, vcc, 0, v127, vcc
	global_load_dwordx4 v[68:71], v[68:69], off offset:384
	s_nop 0
	global_load_dwordx4 v[88:91], v[88:89], off offset:384
	s_nop 0
	global_load_dwordx4 v[92:95], v[92:93], off offset:384
	s_nop 0
	global_load_dwordx4 v[96:99], v[126:127], off offset:384
	s_nop 0
	global_load_dwordx4 v[122:125], v[122:123], off offset:384
	s_nop 0
	global_load_dwordx4 v[130:133], v[128:129], off offset:384
	v_add_co_u32_e32 v128, vcc, s42, v126
	s_nop 1
	v_addc_co_u32_e32 v129, vcc, 0, v127, vcc
	v_add_co_u32_e32 v126, vcc, s43, v126
	s_nop 1
	v_addc_co_u32_e32 v127, vcc, 0, v127, vcc
	global_load_dwordx4 v[134:137], v[128:129], off offset:384
	global_load_dwordx4 v[138:141], v[126:127], off offset:384
	ds_read_b128 v[178:181], v66
	ds_read_b128 v[182:185], v66 offset:32
	ds_read_b128 v[186:189], v72 offset:18432
	ds_read_b128 v[190:193], v72 offset:18464
	ds_read_b128 v[194:197], v72 offset:23040
	ds_read_b128 v[198:201], v72 offset:23072
	ds_read_b128 v[202:205], v72 offset:27648
	ds_read_b128 v[206:209], v72 offset:27680
	ds_read_b128 v[210:213], v72 offset:32256
	ds_read_b128 v[214:217], v72 offset:32288
	ds_read_b128 v[218:221], v66 offset:64
	ds_read_b128 v[222:225], v66 offset:96
	ds_read_b128 v[226:229], v72 offset:18496
	ds_read_b128 v[230:233], v72 offset:18528
	ds_read_b128 v[234:237], v72 offset:23104
	ds_read_b128 v[238:241], v72 offset:23136
	ds_read_b128 v[242:245], v72 offset:27712
	ds_read_b128 v[246:249], v72 offset:27744
	ds_read_b128 v[250:253], v72 offset:32320
	ds_read_b128 v[126:129], v72 offset:32352
	s_setprio 2
	s_waitcnt lgkmcnt(14)
	v_mfma_f32_32x32x16_bf16 v[48:63], v[178:181], v[186:189], v[48:63]
	v_mfma_f32_32x32x16_bf16 v[32:47], v[178:181], v[194:197], v[32:47]
	s_waitcnt lgkmcnt(13)
	v_mfma_f32_32x32x16_bf16 v[16:31], v[178:181], v[202:205], v[16:31]
	s_waitcnt lgkmcnt(11)
	v_mfma_f32_32x32x16_bf16 v[0:15], v[178:181], v[210:213], v[0:15]
	v_mfma_f32_32x32x16_bf16 v[48:63], v[182:185], v[190:193], v[48:63]
	v_mfma_f32_32x32x16_bf16 v[32:47], v[182:185], v[198:201], v[32:47]
	v_mfma_f32_32x32x16_bf16 v[16:31], v[182:185], v[206:209], v[16:31]
	s_waitcnt lgkmcnt(10)
	v_mfma_f32_32x32x16_bf16 v[0:15], v[182:185], v[214:217], v[0:15]
	s_waitcnt lgkmcnt(7)
	v_mfma_f32_32x32x16_bf16 v[48:63], v[218:221], v[226:229], v[48:63]
	s_waitcnt lgkmcnt(5)
	v_mfma_f32_32x32x16_bf16 v[32:47], v[218:221], v[234:237], v[32:47]
	s_waitcnt lgkmcnt(3)
	v_mfma_f32_32x32x16_bf16 v[16:31], v[218:221], v[242:245], v[16:31]
	s_waitcnt lgkmcnt(1)
	v_mfma_f32_32x32x16_bf16 v[0:15], v[218:221], v[250:253], v[0:15]
	v_mfma_f32_32x32x16_bf16 v[48:63], v[222:225], v[230:233], v[48:63]
	v_mfma_f32_32x32x16_bf16 v[32:47], v[222:225], v[238:241], v[32:47]
	v_mfma_f32_32x32x16_bf16 v[16:31], v[222:225], v[246:249], v[16:31]
	s_waitcnt lgkmcnt(0)
	v_mfma_f32_32x32x16_bf16 v[0:15], v[222:225], v[126:129], v[0:15]
	s_setprio 0
	s_barrier
; DI void gemm_mainloop(const bf16* __restrict__ A, int lda, const bf16* __restrict__ Bt, int ldb, int K, int m0, int n0,
;                       bf16* As, bf16* Bs, f32x16& acc0, f32x16& acc1, f32x16& acc2, f32x16& acc3) {
;     ...
;   for (int k0 = 0; k0 < K; k0 += 128) {
;     __syncthreads();
;     gt_store(t0, asw, bsw);
;     __syncthreads();
;     if (k0 + 128 < K) gt_load(t0, ap, bp, lda, ldb, KW(k0 + 128));
;     gt_compute(asr, bsr, acc0, acc1, acc2, acc3);
;     __syncthreads();
;     gt_store(t1, asw, bsw);
;     __syncthreads();
;     if (k0 + 192 < K) gt_load(t1, ap, bp, lda, ldb, KW(k0 + 192));
;     gt_compute(asr, bsr, acc0, acc1, acc2, acc3);
;   }
;     ...
;     } else if constexpr (EPI == EPI_MLA_KV) {
;       __syncthreads();
;       const int hh = nt >> 1;
;       if ((nt & 1) == 0) {
	s_waitcnt vmcnt(13)
	ds_write_b128 v64, v[150:153]
	ds_write_b128 v64, v[142:145] offset:4608
	ds_write_b128 v64, v[146:149] offset:9216
	s_waitcnt vmcnt(11)
	ds_write_b128 v64, v[162:165] offset:13824
	ds_write_b128 v64, v[154:157] offset:18432
	s_waitcnt vmcnt(10)
	ds_write_b128 v64, v[166:169] offset:23040
	s_waitcnt vmcnt(9)
	ds_write_b128 v64, v[170:173] offset:27648
	s_waitcnt vmcnt(8)
	ds_write_b128 v64, v[174:177] offset:32256
	s_waitcnt lgkmcnt(0)
	s_barrier
	ds_read_b128 v[126:129], v66
	ds_read_b128 v[142:145], v66 offset:32
	ds_read_b128 v[146:149], v72 offset:18432
	ds_read_b128 v[150:153], v72 offset:18464
	ds_read_b128 v[154:157], v72 offset:23040
	ds_read_b128 v[162:165], v72 offset:23072
	ds_read_b128 v[166:169], v72 offset:27648
	ds_read_b128 v[170:173], v72 offset:27680
	ds_read_b128 v[174:177], v72 offset:32256
	ds_read_b128 v[178:181], v72 offset:32288
	ds_read_b128 v[182:185], v66 offset:64
	ds_read_b128 v[186:189], v66 offset:96
	ds_read_b128 v[190:193], v72 offset:18496
	ds_read_b128 v[194:197], v72 offset:18528
	ds_read_b128 v[198:201], v72 offset:23104
	ds_read_b128 v[202:205], v72 offset:23136
	ds_read_b128 v[206:209], v72 offset:27712
	ds_read_b128 v[210:213], v72 offset:27744
	ds_read_b128 v[214:217], v72 offset:32320
	ds_read_b128 v[218:221], v72 offset:32352
	s_setprio 2
	s_waitcnt lgkmcnt(14)
	v_mfma_f32_32x32x16_bf16 v[48:63], v[126:129], v[146:149], v[48:63]
	v_mfma_f32_32x32x16_bf16 v[32:47], v[126:129], v[154:157], v[32:47]
	s_waitcnt lgkmcnt(13)
	v_mfma_f32_32x32x16_bf16 v[16:31], v[126:129], v[166:169], v[16:31]
	s_waitcnt lgkmcnt(11)
	v_mfma_f32_32x32x16_bf16 v[0:15], v[126:129], v[174:177], v[0:15]
	v_mfma_f32_32x32x16_bf16 v[48:63], v[142:145], v[150:153], v[48:63]
	v_mfma_f32_32x32x16_bf16 v[32:47], v[142:145], v[162:165], v[32:47]
	v_mfma_f32_32x32x16_bf16 v[16:31], v[142:145], v[170:173], v[16:31]
	s_waitcnt lgkmcnt(10)
	v_mfma_f32_32x32x16_bf16 v[0:15], v[142:145], v[178:181], v[0:15]
	s_waitcnt lgkmcnt(7)
	v_mfma_f32_32x32x16_bf16 v[48:63], v[182:185], v[190:193], v[48:63]
	s_waitcnt lgkmcnt(5)
	v_mfma_f32_32x32x16_bf16 v[32:47], v[182:185], v[198:201], v[32:47]
	s_waitcnt lgkmcnt(3)
	v_mfma_f32_32x32x16_bf16 v[16:31], v[182:185], v[206:209], v[16:31]
	s_waitcnt lgkmcnt(1)
	v_mfma_f32_32x32x16_bf16 v[0:15], v[182:185], v[214:217], v[0:15]
	v_mfma_f32_32x32x16_bf16 v[48:63], v[186:189], v[194:197], v[48:63]
	v_mfma_f32_32x32x16_bf16 v[32:47], v[186:189], v[202:205], v[32:47]
	v_mfma_f32_32x32x16_bf16 v[16:31], v[186:189], v[210:213], v[16:31]
	s_waitcnt lgkmcnt(0)
	v_mfma_f32_32x32x16_bf16 v[0:15], v[186:189], v[218:221], v[0:15]
	s_setprio 0
	s_barrier
	s_waitcnt vmcnt(5)
	ds_write_b128 v64, v[92:95]
	ds_write_b128 v64, v[68:71] offset:4608
	ds_write_b128 v64, v[88:91] offset:9216
	s_waitcnt vmcnt(3)
	ds_write_b128 v64, v[122:125] offset:13824
	ds_write_b128 v64, v[96:99] offset:18432
	s_waitcnt vmcnt(2)
	ds_write_b128 v64, v[130:133] offset:23040
	s_waitcnt vmcnt(1)
	ds_write_b128 v64, v[134:137] offset:27648
	s_waitcnt vmcnt(0)
	ds_write_b128 v64, v[138:141] offset:32256
	s_waitcnt lgkmcnt(0)
	s_barrier
	ds_read_b128 v[68:71], v66
	ds_read_b128 v[88:91], v66 offset:32
	ds_read_b128 v[92:95], v72 offset:18432
	ds_read_b128 v[96:99], v72 offset:18464
	ds_read_b128 v[122:125], v72 offset:23040
	ds_read_b128 v[126:129], v72 offset:23072
	ds_read_b128 v[130:133], v72 offset:27648
	ds_read_b128 v[134:137], v72 offset:27680
	ds_read_b128 v[138:141], v72 offset:32256
	ds_read_b128 v[142:145], v72 offset:32288
	ds_read_b128 v[146:149], v66 offset:64
	ds_read_b128 v[64:67], v66 offset:96
	ds_read_b128 v[150:153], v72 offset:18496
	ds_read_b128 v[154:157], v72 offset:18528
	ds_read_b128 v[162:165], v72 offset:23104
	ds_read_b128 v[166:169], v72 offset:23136
	ds_read_b128 v[170:173], v72 offset:27712
	ds_read_b128 v[174:177], v72 offset:27744
	ds_read_b128 v[178:181], v72 offset:32320
	ds_read_b128 v[182:185], v72 offset:32352
	s_setprio 2
	s_waitcnt lgkmcnt(14)
	v_mfma_f32_32x32x16_bf16 v[48:63], v[68:71], v[92:95], v[48:63]
	v_mfma_f32_32x32x16_bf16 v[32:47], v[68:71], v[122:125], v[32:47]
	s_waitcnt lgkmcnt(13)
	v_mfma_f32_32x32x16_bf16 v[16:31], v[68:71], v[130:133], v[16:31]
	s_waitcnt lgkmcnt(11)
	v_mfma_f32_32x32x16_bf16 v[0:15], v[68:71], v[138:141], v[0:15]
	v_mfma_f32_32x32x16_bf16 v[48:63], v[88:91], v[96:99], v[48:63]
	v_mfma_f32_32x32x16_bf16 v[32:47], v[88:91], v[126:129], v[32:47]
	v_mfma_f32_32x32x16_bf16 v[16:31], v[88:91], v[134:137], v[16:31]
	s_waitcnt lgkmcnt(10)
	v_mfma_f32_32x32x16_bf16 v[0:15], v[88:91], v[142:145], v[0:15]
	s_waitcnt lgkmcnt(7)
	v_mfma_f32_32x32x16_bf16 v[48:63], v[146:149], v[150:153], v[48:63]
	s_waitcnt lgkmcnt(5)
	v_mfma_f32_32x32x16_bf16 v[32:47], v[146:149], v[162:165], v[32:47]
	s_waitcnt lgkmcnt(3)
	v_mfma_f32_32x32x16_bf16 v[16:31], v[146:149], v[170:173], v[16:31]
	s_waitcnt lgkmcnt(1)
	v_mfma_f32_32x32x16_bf16 v[0:15], v[146:149], v[178:181], v[0:15]
	v_mfma_f32_32x32x16_bf16 v[48:63], v[64:67], v[154:157], v[48:63]
	v_mfma_f32_32x32x16_bf16 v[32:47], v[64:67], v[166:169], v[32:47]
	v_mfma_f32_32x32x16_bf16 v[16:31], v[64:67], v[174:177], v[16:31]
	s_waitcnt lgkmcnt(0)
	v_mfma_f32_32x32x16_bf16 v[0:15], v[64:67], v[182:185], v[0:15]
	s_setprio 0
	s_and_b32 s0, s0, 0x780
	s_ashr_i32 s18, s1, 1
	s_bitcmp1_b32 s1, 0
	s_cselect_b64 s[48:49], -1, 0
	s_ashr_i32 s1, s28, 1
	s_and_b32 s1, s1, -8
	s_add_i32 s18, s1, s18
	s_ashr_i32 s19, s18, 31
	s_mov_b64 s[28:29], -1
	s_and_b64 vcc, exec, s[48:49]
	s_barrier
;     ...
;       } else {
;         bf16* Vt = (bf16*)(ws + OFF_VT);
; #pragma unroll
;         for (int j = 0; j < 4; ++j)
; #pragma unroll
;           for (int qd = 0; qd < 4; ++qd) {
;             int rl = 32 * w + 8 * qd + 4 * g;
;             int s = (m0 & 2047) + rl;
;             uint2 o;
;             o.x = pack2(acc[j][4 * qd] * rs[rl], acc[j][4 * qd + 1] * rs[rl + 1]);
;             o.y = pack2(acc[j][4 * qd + 2] * rs[rl + 2], acc[j][4 * qd + 3] * rs[rl + 3]);
;             *(uint2*)(Vt + (((size_t)(bidx * 8 + hh) * 32 + (s >> 6)) * 128 + 32 * j + r) * 64 + (s & 63)) = o;
;           }
	s_cbranch_vccz .LBB0_348
	ds_read_b128 v[64:67], v104 offset:40960
	ds_read_b128 v[68:71], v104 offset:40992
	v_add_u32_e32 v72, s0, v102
	s_lshl_b64 s[28:29], s[18:19], 19
	v_mov_b32_e32 v81, v73
	s_waitcnt lgkmcnt(1)
	v_pk_mul_f32 v[88:89], v[48:49], v[64:65]
	v_pk_mul_f32 v[90:91], v[50:51], v[66:67]
	v_cvt_pk_bf16_f32 v88, v88, v89
	v_cvt_pk_bf16_f32 v89, v90, v91
	v_ashrrev_i32_e32 v90, 6, v72
	v_ashrrev_i32_e32 v91, 31, v90
	v_lshlrev_b64 v[90:91], 14, v[90:91]
	v_lshl_add_u64 v[90:91], s[10:11], 0, v[90:91]
	v_lshl_add_u64 v[90:91], v[90:91], 0, s[28:29]
	v_lshl_add_u64 v[96:97], v[90:91], 0, v[76:77]
	v_lshl_add_u64 v[90:91], v[96:97], 0, v[80:81]
	global_store_dwordx2 v[90:91], v[88:89], off
	s_waitcnt lgkmcnt(0)
	v_pk_mul_f32 v[88:89], v[52:53], v[68:69]
	v_mov_b32_e32 v83, v73
	v_cvt_pk_bf16_f32 v92, v88, v89
	v_pk_mul_f32 v[88:89], v[54:55], v[70:71]
	v_lshl_add_u64 v[94:95], v[96:97], 0, v[82:83]
	v_cvt_pk_bf16_f32 v93, v88, v89
	ds_read_b128 v[88:91], v104 offset:41024
	global_store_dwordx2 v[94:95], v[92:93], off
	ds_read_b128 v[92:95], v104 offset:41056
	v_mov_b32_e32 v85, v73
	v_mov_b32_e32 v87, v73
	s_waitcnt lgkmcnt(1)
	v_pk_mul_f32 v[98:99], v[56:57], v[88:89]
	v_pk_mul_f32 v[122:123], v[58:59], v[90:91]
	v_cvt_pk_bf16_f32 v98, v98, v99
	v_cvt_pk_bf16_f32 v99, v122, v123
	v_lshl_add_u64 v[122:123], v[96:97], 0, v[84:85]
	global_store_dwordx2 v[122:123], v[98:99], off
	s_waitcnt lgkmcnt(0)
	v_pk_mul_f32 v[98:99], v[60:61], v[92:93]
	v_pk_mul_f32 v[122:123], v[62:63], v[94:95]
	v_cvt_pk_bf16_f32 v98, v98, v99
	v_cvt_pk_bf16_f32 v99, v122, v123
	v_lshl_add_u64 v[122:123], v[96:97], 0, v[86:87]
	global_store_dwordx2 v[122:123], v[98:99], off
	v_pk_mul_f32 v[98:99], v[32:33], v[64:65]
	v_pk_mul_f32 v[122:123], v[34:35], v[66:67]
	v_cvt_pk_bf16_f32 v98, v98, v99
	v_cvt_pk_bf16_f32 v99, v122, v123
	v_lshl_add_u64 v[122:123], v[96:97], 0, s[12:13]
	v_lshl_add_u64 v[124:125], v[122:123], 0, v[80:81]
	global_store_dwordx2 v[124:125], v[98:99], off
	v_pk_mul_f32 v[98:99], v[36:37], v[68:69]
	v_pk_mul_f32 v[124:125], v[38:39], v[70:71]
	v_cvt_pk_bf16_f32 v98, v98, v99
	v_cvt_pk_bf16_f32 v99, v124, v125
	v_lshl_add_u64 v[124:125], v[122:123], 0, v[82:83]
	global_store_dwordx2 v[124:125], v[98:99], off
	v_pk_mul_f32 v[98:99], v[40:41], v[88:89]
	v_pk_mul_f32 v[124:125], v[42:43], v[90:91]
	v_cvt_pk_bf16_f32 v98, v98, v99
	v_cvt_pk_bf16_f32 v99, v124, v125
	v_lshl_add_u64 v[124:125], v[122:123], 0, v[84:85]
	global_store_dwordx2 v[124:125], v[98:99], off
	v_pk_mul_f32 v[98:99], v[44:45], v[92:93]
	v_pk_mul_f32 v[124:125], v[46:47], v[94:95]
	v_cvt_pk_bf16_f32 v98, v98, v99
	v_cvt_pk_bf16_f32 v99, v124, v125
	v_lshl_add_u64 v[122:123], v[122:123], 0, v[86:87]
	global_store_dwordx2 v[122:123], v[98:99], off
	v_pk_mul_f32 v[98:99], v[16:17], v[64:65]
	v_pk_mul_f32 v[122:123], v[18:19], v[66:67]
	v_pk_mul_f32 v[64:65], v[0:1], v[64:65]
	v_pk_mul_f32 v[66:67], v[2:3], v[66:67]
	v_cvt_pk_bf16_f32 v98, v98, v99
	v_cvt_pk_bf16_f32 v99, v122, v123
	v_lshl_add_u64 v[122:123], v[96:97], 0, s[14:15]
	v_cvt_pk_bf16_f32 v64, v64, v65
	v_cvt_pk_bf16_f32 v65, v66, v67
	v_lshl_add_u64 v[66:67], v[96:97], 0, s[16:17]
	v_lshl_add_u64 v[124:125], v[122:123], 0, v[80:81]
	v_lshl_add_u64 v[96:97], v[66:67], 0, v[80:81]
	global_store_dwordx2 v[124:125], v[98:99], off
	v_pk_mul_f32 v[98:99], v[20:21], v[68:69]
	v_pk_mul_f32 v[124:125], v[22:23], v[70:71]
	global_store_dwordx2 v[96:97], v[64:65], off
	v_pk_mul_f32 v[64:65], v[4:5], v[68:69]
	v_pk_mul_f32 v[68:69], v[6:7], v[70:71]
	v_cvt_pk_bf16_f32 v98, v98, v99
	v_cvt_pk_bf16_f32 v99, v124, v125
	v_lshl_add_u64 v[124:125], v[122:123], 0, v[82:83]
	v_cvt_pk_bf16_f32 v64, v64, v65
	v_cvt_pk_bf16_f32 v65, v68, v69
	v_lshl_add_u64 v[68:69], v[66:67], 0, v[82:83]
	global_store_dwordx2 v[124:125], v[98:99], off
	v_pk_mul_f32 v[98:99], v[24:25], v[88:89]
	v_pk_mul_f32 v[124:125], v[26:27], v[90:91]
	global_store_dwordx2 v[68:69], v[64:65], off
	v_pk_mul_f32 v[64:65], v[8:9], v[88:89]
	v_pk_mul_f32 v[68:69], v[10:11], v[90:91]
	v_cvt_pk_bf16_f32 v98, v98, v99
	v_cvt_pk_bf16_f32 v99, v124, v125
	v_lshl_add_u64 v[124:125], v[122:123], 0, v[84:85]
	v_cvt_pk_bf16_f32 v64, v64, v65
	v_cvt_pk_bf16_f32 v65, v68, v69
	v_lshl_add_u64 v[68:69], v[66:67], 0, v[84:85]
	global_store_dwordx2 v[124:125], v[98:99], off
	v_pk_mul_f32 v[98:99], v[28:29], v[92:93]
	v_pk_mul_f32 v[124:125], v[30:31], v[94:95]
	global_store_dwordx2 v[68:69], v[64:65], off
	v_pk_mul_f32 v[64:65], v[12:13], v[92:93]
	v_pk_mul_f32 v[68:69], v[14:15], v[94:95]
	v_cvt_pk_bf16_f32 v98, v98, v99
	v_cvt_pk_bf16_f32 v99, v124, v125
	v_lshl_add_u64 v[122:123], v[122:123], 0, v[86:87]
	v_cvt_pk_bf16_f32 v64, v64, v65
	v_cvt_pk_bf16_f32 v65, v68, v69
	v_lshl_add_u64 v[66:67], v[66:67], 0, v[86:87]
	global_store_dwordx2 v[122:123], v[98:99], off
	global_store_dwordx2 v[66:67], v[64:65], off
	s_mov_b64 s[28:29], 0
